# P1/P5: per-tile epilogue align and re-stagger barriers removed for tiles that have a successor (lead wave group starts its epilogue while the other group finishes its last MFMA phase); kept on the las
# baseline (speedup 1.0000x reference)
; #define PG8_STAGE(bufoff, gbase, voff) do { _Pragma("unroll") for (int _i = 0; _i < 2; ++_i) \
;         __builtin_amdgcn_global_load_lds((const __attribute__((address_space(1))) unsigned*)((const char*)(gbase) + (voff)[_i]), (LAS unsigned*)(lds + (bufoff) + ldsw + _i * 8192), 16, 0, 0); } while (0)
; #define PG8_LDA(dst, b, h) do { _Pragma("unroll") for (int m = 0; m < 4; ++m) _Pragma("unroll") for (int k = 0; k < 2; ++k) dst[m][k] = *(const LAS bf16x8*)(lds + PG8_SA(b, h) + aoff + m * 2048 + k * 1024); } while (0)
; #define PG8_LDB(dst, b, h) do { _Pragma("unroll") for (int n = 0; n < 2; ++n) _Pragma("unroll") for (int k = 0; k < 2; ++k) dst[n][k] = *(const LAS bf16x8*)(lds + PG8_SB(b, h) + boff + n * 2048 + k * 1024); } while (0)
; #define PG8_MMA(ai, bj, At, Bt) do { __builtin_amdgcn_s_setprio(1); _Pragma("unroll") for (int m = 0; m < 4; ++m) _Pragma("unroll") for (int n = 0; n < 2; ++n) _Pragma("unroll") for (int k = 0; k < 2; ++k) \
;         acc[ai][bj][m][n] = __builtin_amdgcn_mfma_f32_16x16x32_bf16(Bt[n][k], At[m][k], acc[ai][bj][m][n], 0, 0, 0); __builtin_amdgcn_s_setprio(0); } while (0)
; #define PG8_WAIT_V(n) asm volatile("s_waitcnt vmcnt(" #n ")" ::: "memory")
; #define PG8_WAIT_L(n) asm volatile("s_waitcnt lgkmcnt(" #n ")" ::: "memory")
; #define PG8_BAR __builtin_amdgcn_s_barrier()
; #define PG8_SCHED __builtin_amdgcn_sched_barrier(0)
; template <class Epi, class SchedT, bool ALIGN_EPI, bool SP2>
; __device__ __forceinline__ void gemm_phase(LAS unsigned char* lds, const int ldk, const int nt, const SchedT& S, const Epi& E) {
;     ...
;             PG8_LDB(B0, 0, 0); PG8_LDB(B1, 0, 1); PG8_SCHED; PG8_LDA(At, 0, 0); PG8_STAGE(PG8_SA(1, 1), a1 + hstep, voffA);
;             PG8_WAIT_V(8); PG8_WAIT_L(0); PG8_BAR; PG8_MMA(0, 0, At, B0); PG8_MMA(0, 1, At, B1); PG8_BAR; PG8_SCHED;
;             PG8_LDA(At, 0, 1); PG8_STAGE(PG8_SB(0, 0), b2, voffB); PG8_STAGE(PG8_SB(0, 1), b2 + hstepB, voffB); PG8_STAGE(PG8_SA(0, 0), a2, voffA);
.LBB0_123:
	s_add_u32 s12, s0, 0xfff80080
	s_addc_u32 s13, s1, -1
	s_add_i32 s34, 0, 0x10000
	s_cmp_eq_u32 s21, 28
	s_cselect_b32 s17, s61, s13
	s_cselect_b32 s16, s60, s12
	v_add_u32_e32 v0, s34, v212
	s_cselect_b32 s13, s31, s19
	s_cselect_b32 s12, s30, s18
	s_add_i32 s38, 0, 0x14000
	s_waitcnt lgkmcnt(0)
	ds_read_b128 v[132:135], v0
	ds_read_b128 v[136:139], v0 offset:1024
	ds_read_b128 v[140:143], v0 offset:2048
	ds_read_b128 v[144:147], v0 offset:3072
	v_add_u32_e32 v0, s38, v212
	ds_read_b128 v[148:151], v0
	ds_read_b128 v[152:155], v0 offset:1024
	ds_read_b128 v[184:187], v0 offset:2048
	ds_read_b128 v[188:191], v0 offset:3072
	v_lshl_add_u64 v[2:3], s[0:1], 0, v[180:181]
	s_add_i32 m0, s88, 0xc000
	ds_read_b128 v[192:195], v216
	ds_read_b128 v[196:199], v216 offset:1024
	ds_read_b128 v[200:203], v216 offset:2048
	ds_read_b128 v[204:207], v216 offset:3072
	ds_read_b128 v[218:221], v216 offset:4096
	ds_read_b128 v[222:225], v216 offset:5120
	ds_read_b128 v[226:229], v216 offset:6144
	ds_read_b128 v[230:233], v216 offset:7168
	global_load_lds_dwordx4 v[2:3], off
	v_lshl_add_u64 v[2:3], s[0:1], 0, v[182:183]
	s_add_i32 m0, s88, 0xe000
	s_nop 0
	global_load_lds_dwordx4 v[2:3], off
	s_waitcnt vmcnt(8)
	s_waitcnt lgkmcnt(0)
	s_barrier
	s_setprio 1
	s_waitcnt lgkmcnt(0)
	v_mfma_f32_16x16x32_bf16 v[128:131], v[132:135], v[192:195], v[128:131]
	v_mfma_f32_16x16x32_bf16 v[124:127], v[140:143], v[192:195], v[124:127]
	v_mfma_f32_16x16x32_bf16 v[112:115], v[132:135], v[200:203], v[112:115]
	v_mfma_f32_16x16x32_bf16 v[108:111], v[140:143], v[200:203], v[108:111]
	v_mfma_f32_16x16x32_bf16 v[96:99], v[132:135], v[218:221], v[96:99]
	v_mfma_f32_16x16x32_bf16 v[92:95], v[140:143], v[218:221], v[92:95]
	v_mfma_f32_16x16x32_bf16 v[80:83], v[132:135], v[226:229], v[80:83]
	v_mfma_f32_16x16x32_bf16 v[76:79], v[140:143], v[226:229], v[76:79]
	v_mfma_f32_16x16x32_bf16 v[128:131], v[136:139], v[196:199], v[128:131]
	v_mfma_f32_16x16x32_bf16 v[124:127], v[144:147], v[196:199], v[124:127]
	v_mfma_f32_16x16x32_bf16 v[112:115], v[136:139], v[204:207], v[112:115]
	v_mfma_f32_16x16x32_bf16 v[108:111], v[144:147], v[204:207], v[108:111]
	v_mfma_f32_16x16x32_bf16 v[96:99], v[136:139], v[222:225], v[96:99]
	v_mfma_f32_16x16x32_bf16 v[92:95], v[144:147], v[222:225], v[92:95]
	v_mfma_f32_16x16x32_bf16 v[80:83], v[136:139], v[230:233], v[80:83]
	v_mfma_f32_16x16x32_bf16 v[76:79], v[144:147], v[230:233], v[76:79]
	v_mfma_f32_16x16x32_bf16 v[120:123], v[148:151], v[192:195], v[120:123]
	v_mfma_f32_16x16x32_bf16 v[116:119], v[184:187], v[192:195], v[116:119]
	v_mfma_f32_16x16x32_bf16 v[104:107], v[148:151], v[200:203], v[104:107]
	v_mfma_f32_16x16x32_bf16 v[100:103], v[184:187], v[200:203], v[100:103]
	v_mfma_f32_16x16x32_bf16 v[88:91], v[148:151], v[218:221], v[88:91]
	v_mfma_f32_16x16x32_bf16 v[84:87], v[184:187], v[218:221], v[84:87]
	v_mfma_f32_16x16x32_bf16 v[72:75], v[148:151], v[226:229], v[72:75]
	v_mfma_f32_16x16x32_bf16 v[68:71], v[184:187], v[226:229], v[68:71]
	v_mfma_f32_16x16x32_bf16 v[120:123], v[152:155], v[196:199], v[120:123]
	v_mfma_f32_16x16x32_bf16 v[116:119], v[188:191], v[196:199], v[116:119]
	v_mfma_f32_16x16x32_bf16 v[104:107], v[152:155], v[204:207], v[104:107]
	v_mfma_f32_16x16x32_bf16 v[100:103], v[188:191], v[204:207], v[100:103]
	v_mfma_f32_16x16x32_bf16 v[88:91], v[152:155], v[222:225], v[88:91]
	v_mfma_f32_16x16x32_bf16 v[84:87], v[188:191], v[222:225], v[84:87]
	v_mfma_f32_16x16x32_bf16 v[72:75], v[152:155], v[230:233], v[72:75]
	v_mfma_f32_16x16x32_bf16 v[68:71], v[188:191], v[230:233], v[68:71]
	s_setprio 0
	s_barrier
	s_add_i32 s34, s34, s87
	v_lshl_add_u64 v[208:209], s[12:13], 0, v[158:159]
	s_mov_b32 m0, s34
	ds_read_b128 v[192:195], v216 offset:16384
	ds_read_b128 v[196:199], v216 offset:17408
	ds_read_b128 v[200:203], v216 offset:18432
	ds_read_b128 v[204:207], v216 offset:19456
	ds_read_b128 v[218:221], v216 offset:20480
	ds_read_b128 v[222:225], v216 offset:21504
	ds_read_b128 v[226:229], v216 offset:22528
	ds_read_b128 v[230:233], v216 offset:23552
	global_load_lds_dwordx4 v[208:209], off
	s_add_i32 m0, s34, 0x2000
	s_add_u32 s34, s12, 0x20000
	v_lshl_add_u64 v[234:235], s[12:13], 0, v[174:175]
	s_addc_u32 s35, s13, 0
	s_add_i32 s38, s38, s87
	global_load_lds_dwordx4 v[234:235], off
	v_lshl_add_u64 v[2:3], s[34:35], 0, v[158:159]
	s_mov_b32 m0, s38
	v_lshl_add_u64 v[236:237], s[16:17], 0, v[156:157]
	global_load_lds_dwordx4 v[2:3], off
	v_lshl_add_u64 v[2:3], s[34:35], 0, v[174:175]
	s_add_i32 m0, s38, 0x2000
	v_lshl_add_u64 v[238:239], s[16:17], 0, v[160:161]
	global_load_lds_dwordx4 v[2:3], off
	s_mov_b32 m0, s88
	s_nop 0
	global_load_lds_dwordx4 v[236:237], off
	s_mov_b32 m0, s89
	s_nop 0
	global_load_lds_dwordx4 v[238:239], off
	s_waitcnt vmcnt(8)
	s_waitcnt lgkmcnt(0)
	s_barrier
; #define PG8_STAGE(bufoff, gbase, voff) do { _Pragma("unroll") for (int _i = 0; _i < 2; ++_i) \
;         __builtin_amdgcn_global_load_lds((const __attribute__((address_space(1))) unsigned*)((const char*)(gbase) + (voff)[_i]), (LAS unsigned*)(lds + (bufoff) + ldsw + _i * 8192), 16, 0, 0); } while (0)
; #define PG8_LDA(dst, b, h) do { _Pragma("unroll") for (int m = 0; m < 4; ++m) _Pragma("unroll") for (int k = 0; k < 2; ++k) dst[m][k] = *(const LAS bf16x8*)(lds + PG8_SA(b, h) + aoff + m * 2048 + k * 1024); } while (0)
; #define PG8_LDB(dst, b, h) do { _Pragma("unroll") for (int n = 0; n < 2; ++n) _Pragma("unroll") for (int k = 0; k < 2; ++k) dst[n][k] = *(const LAS bf16x8*)(lds + PG8_SB(b, h) + boff + n * 2048 + k * 1024); } while (0)
; #define PG8_MMA(ai, bj, At, Bt) do { __builtin_amdgcn_s_setprio(1); _Pragma("unroll") for (int m = 0; m < 4; ++m) _Pragma("unroll") for (int n = 0; n < 2; ++n) _Pragma("unroll") for (int k = 0; k < 2; ++k) \
;         acc[ai][bj][m][n] = __builtin_amdgcn_mfma_f32_16x16x32_bf16(Bt[n][k], At[m][k], acc[ai][bj][m][n], 0, 0, 0); __builtin_amdgcn_s_setprio(0); } while (0)
; #define PG8_WAIT_V(n) asm volatile("s_waitcnt vmcnt(" #n ")" ::: "memory")
; #define PG8_WAIT_L(n) asm volatile("s_waitcnt lgkmcnt(" #n ")" ::: "memory")
; #define PG8_BAR __builtin_amdgcn_s_barrier()
; #define PG8_SCHED __builtin_amdgcn_sched_barrier(0)
; template <class Epi, class SchedT, bool ALIGN_EPI, bool SP2>
; __device__ __forceinline__ void gemm_phase(LAS unsigned char* lds, const int ldk, const int nt, const SchedT& S, const Epi& E) {
;     ...
;             PG8_LDA(At, 0, 1); PG8_STAGE(PG8_SB(0, 0), b2, voffB); PG8_STAGE(PG8_SB(0, 1), b2 + hstepB, voffB); PG8_STAGE(PG8_SA(0, 0), a2, voffA);
;             PG8_WAIT_V(8); PG8_WAIT_L(0); PG8_BAR; PG8_MMA(1, 0, At, B0); PG8_MMA(1, 1, At, B1); PG8_BAR; PG8_SCHED;
;             PG8_LDB(B0, 1, 0); PG8_LDB(B1, 1, 1); PG8_SCHED; PG8_LDA(At, 1, 0); PG8_STAGE(PG8_SA(0, 1), a2 + hstep, voffA);
;             PG8_WAIT_V(8); PG8_WAIT_L(0); PG8_BAR; PG8_MMA(0, 0, At, B0); PG8_MMA(0, 1, At, B1); PG8_BAR; PG8_SCHED;
	s_setprio 1
	s_waitcnt lgkmcnt(0)
	v_mfma_f32_16x16x32_bf16 v[64:67], v[132:135], v[192:195], v[64:67]
	v_mfma_f32_16x16x32_bf16 v[60:63], v[140:143], v[192:195], v[60:63]
	v_mfma_f32_16x16x32_bf16 v[48:51], v[132:135], v[200:203], v[48:51]
	v_mfma_f32_16x16x32_bf16 v[44:47], v[140:143], v[200:203], v[44:47]
	v_mfma_f32_16x16x32_bf16 v[32:35], v[132:135], v[218:221], v[32:35]
	v_mfma_f32_16x16x32_bf16 v[28:31], v[140:143], v[218:221], v[28:31]
	v_mfma_f32_16x16x32_bf16 v[16:19], v[132:135], v[226:229], v[16:19]
	v_mfma_f32_16x16x32_bf16 v[12:15], v[140:143], v[226:229], v[12:15]
	v_mfma_f32_16x16x32_bf16 v[64:67], v[136:139], v[196:199], v[64:67]
	v_mfma_f32_16x16x32_bf16 v[60:63], v[144:147], v[196:199], v[60:63]
	v_mfma_f32_16x16x32_bf16 v[48:51], v[136:139], v[204:207], v[48:51]
	v_mfma_f32_16x16x32_bf16 v[44:47], v[144:147], v[204:207], v[44:47]
	v_mfma_f32_16x16x32_bf16 v[32:35], v[136:139], v[222:225], v[32:35]
	v_mfma_f32_16x16x32_bf16 v[28:31], v[144:147], v[222:225], v[28:31]
	v_mfma_f32_16x16x32_bf16 v[16:19], v[136:139], v[230:233], v[16:19]
	v_mfma_f32_16x16x32_bf16 v[12:15], v[144:147], v[230:233], v[12:15]
	v_mfma_f32_16x16x32_bf16 v[56:59], v[148:151], v[192:195], v[56:59]
	v_mfma_f32_16x16x32_bf16 v[52:55], v[184:187], v[192:195], v[52:55]
	v_mfma_f32_16x16x32_bf16 v[40:43], v[148:151], v[200:203], v[40:43]
	v_mfma_f32_16x16x32_bf16 v[36:39], v[184:187], v[200:203], v[36:39]
	v_mfma_f32_16x16x32_bf16 v[24:27], v[148:151], v[218:221], v[24:27]
	v_mfma_f32_16x16x32_bf16 v[20:23], v[184:187], v[218:221], v[20:23]
	v_mfma_f32_16x16x32_bf16 v[8:11], v[148:151], v[226:229], v[8:11]
	v_mfma_f32_16x16x32_bf16 v[2:5], v[184:187], v[226:229], v[4:7]
	v_mfma_f32_16x16x32_bf16 v[56:59], v[152:155], v[196:199], v[56:59]
	v_mfma_f32_16x16x32_bf16 v[52:55], v[188:191], v[196:199], v[52:55]
	v_mfma_f32_16x16x32_bf16 v[40:43], v[152:155], v[204:207], v[40:43]
	v_mfma_f32_16x16x32_bf16 v[36:39], v[188:191], v[204:207], v[36:39]
	v_mfma_f32_16x16x32_bf16 v[24:27], v[152:155], v[222:225], v[24:27]
	v_mfma_f32_16x16x32_bf16 v[20:23], v[188:191], v[222:225], v[20:23]
	v_mfma_f32_16x16x32_bf16 v[8:11], v[152:155], v[230:233], v[8:11]
	v_mfma_f32_16x16x32_bf16 v[2:5], v[188:191], v[230:233], v[2:5]
	s_setprio 0
	s_barrier
	s_add_i32 s34, 0, 0x18000
	v_add_u32_e32 v0, s34, v212
	s_add_i32 s35, 0, 0x1c000
	ds_read_b128 v[132:135], v0
	ds_read_b128 v[136:139], v0 offset:1024
	ds_read_b128 v[140:143], v0 offset:2048
	ds_read_b128 v[144:147], v0 offset:3072
	v_add_u32_e32 v0, s35, v212
	ds_read_b128 v[148:151], v0
	ds_read_b128 v[152:155], v0 offset:1024
	ds_read_b128 v[184:187], v0 offset:2048
	ds_read_b128 v[188:191], v0 offset:3072
	s_add_u32 s16, s16, 0x80000
	s_addc_u32 s17, s17, 0
	s_mov_b32 m0, s90
	v_lshl_add_u64 v[6:7], s[16:17], 0, v[156:157]
	ds_read_b128 v[192:195], v216 offset:32768
	ds_read_b128 v[196:199], v216 offset:33792
	ds_read_b128 v[200:203], v216 offset:34816
	ds_read_b128 v[204:207], v216 offset:35840
	ds_read_b128 v[218:221], v216 offset:36864
	ds_read_b128 v[222:225], v216 offset:37888
	ds_read_b128 v[226:229], v216 offset:38912
	ds_read_b128 v[230:233], v216 offset:39936
	global_load_lds_dwordx4 v[6:7], off
	v_lshl_add_u64 v[6:7], s[16:17], 0, v[160:161]
	s_mov_b32 m0, s91
	s_nop 0
	global_load_lds_dwordx4 v[6:7], off
	s_waitcnt vmcnt(8)
	s_waitcnt lgkmcnt(0)
	s_barrier
	s_setprio 1
	s_waitcnt lgkmcnt(0)
	v_mfma_f32_16x16x32_bf16 v[128:131], v[132:135], v[192:195], v[128:131]
	v_mfma_f32_16x16x32_bf16 v[124:127], v[140:143], v[192:195], v[124:127]
	v_mfma_f32_16x16x32_bf16 v[112:115], v[132:135], v[200:203], v[112:115]
	v_mfma_f32_16x16x32_bf16 v[108:111], v[140:143], v[200:203], v[108:111]
	v_mfma_f32_16x16x32_bf16 v[96:99], v[132:135], v[218:221], v[96:99]
	v_mfma_f32_16x16x32_bf16 v[92:95], v[140:143], v[218:221], v[92:95]
	v_mfma_f32_16x16x32_bf16 v[80:83], v[132:135], v[226:229], v[80:83]
	v_mfma_f32_16x16x32_bf16 v[76:79], v[140:143], v[226:229], v[76:79]
	v_mfma_f32_16x16x32_bf16 v[128:131], v[136:139], v[196:199], v[128:131]
	v_mfma_f32_16x16x32_bf16 v[124:127], v[144:147], v[196:199], v[124:127]
	v_mfma_f32_16x16x32_bf16 v[112:115], v[136:139], v[204:207], v[112:115]
	v_mfma_f32_16x16x32_bf16 v[108:111], v[144:147], v[204:207], v[108:111]
	v_mfma_f32_16x16x32_bf16 v[96:99], v[136:139], v[222:225], v[96:99]
	v_mfma_f32_16x16x32_bf16 v[92:95], v[144:147], v[222:225], v[92:95]
	v_mfma_f32_16x16x32_bf16 v[80:83], v[136:139], v[230:233], v[80:83]
	v_mfma_f32_16x16x32_bf16 v[76:79], v[144:147], v[230:233], v[76:79]
	v_mfma_f32_16x16x32_bf16 v[120:123], v[148:151], v[192:195], v[120:123]
	v_mfma_f32_16x16x32_bf16 v[116:119], v[184:187], v[192:195], v[116:119]
	v_mfma_f32_16x16x32_bf16 v[104:107], v[148:151], v[200:203], v[104:107]
	v_mfma_f32_16x16x32_bf16 v[100:103], v[184:187], v[200:203], v[100:103]
	v_mfma_f32_16x16x32_bf16 v[88:91], v[148:151], v[218:221], v[88:91]
	v_mfma_f32_16x16x32_bf16 v[84:87], v[184:187], v[218:221], v[84:87]
	v_mfma_f32_16x16x32_bf16 v[72:75], v[148:151], v[226:229], v[72:75]
	v_mfma_f32_16x16x32_bf16 v[68:71], v[184:187], v[226:229], v[68:71]
	v_mfma_f32_16x16x32_bf16 v[120:123], v[152:155], v[196:199], v[120:123]
	v_mfma_f32_16x16x32_bf16 v[116:119], v[188:191], v[196:199], v[116:119]
	v_mfma_f32_16x16x32_bf16 v[104:107], v[152:155], v[204:207], v[104:107]
	v_mfma_f32_16x16x32_bf16 v[100:103], v[188:191], v[204:207], v[100:103]
	v_mfma_f32_16x16x32_bf16 v[88:91], v[152:155], v[222:225], v[88:91]
	v_mfma_f32_16x16x32_bf16 v[84:87], v[188:191], v[222:225], v[84:87]
	v_mfma_f32_16x16x32_bf16 v[72:75], v[152:155], v[230:233], v[72:75]
	v_mfma_f32_16x16x32_bf16 v[68:71], v[188:191], v[230:233], v[68:71]
	s_setprio 0
	s_barrier
; #define PG8_STAGE(bufoff, gbase, voff) do { _Pragma("unroll") for (int _i = 0; _i < 2; ++_i) \
;         __builtin_amdgcn_global_load_lds((const __attribute__((address_space(1))) unsigned*)((const char*)(gbase) + (voff)[_i]), (LAS unsigned*)(lds + (bufoff) + ldsw + _i * 8192), 16, 0, 0); } while (0)
; #define PG8_LDA(dst, b, h) do { _Pragma("unroll") for (int m = 0; m < 4; ++m) _Pragma("unroll") for (int k = 0; k < 2; ++k) dst[m][k] = *(const LAS bf16x8*)(lds + PG8_SA(b, h) + aoff + m * 2048 + k * 1024); } while (0)
; #define PG8_MMA(ai, bj, At, Bt) do { __builtin_amdgcn_s_setprio(1); _Pragma("unroll") for (int m = 0; m < 4; ++m) _Pragma("unroll") for (int n = 0; n < 2; ++n) _Pragma("unroll") for (int k = 0; k < 2; ++k) \
;         acc[ai][bj][m][n] = __builtin_amdgcn_mfma_f32_16x16x32_bf16(Bt[n][k], At[m][k], acc[ai][bj][m][n], 0, 0, 0); __builtin_amdgcn_s_setprio(0); } while (0)
; #define PG8_WAIT_V(n) asm volatile("s_waitcnt vmcnt(" #n ")" ::: "memory")
; #define PG8_WAIT_L(n) asm volatile("s_waitcnt lgkmcnt(" #n ")" ::: "memory")
; #define PG8_BAR __builtin_amdgcn_s_barrier()
; #define PG8_SCHED __builtin_amdgcn_sched_barrier(0)
; template <class Epi, class SchedT, bool ALIGN_EPI, bool SP2>
; __device__ __forceinline__ void gemm_phase(LAS unsigned char* lds, const int ldk, const int nt, const SchedT& S, const Epi& E) {
;     ...
;             PG8_LDA(At, 1, 1); PG8_STAGE(PG8_SB(1, 0), b3, voffB); PG8_STAGE(PG8_SB(1, 1), b3 + hstepB, voffB); PG8_STAGE(PG8_SA(1, 0), a3, voffA);
;             PG8_WAIT_V(8); PG8_WAIT_L(0); PG8_BAR; PG8_MMA(1, 0, At, B0); PG8_MMA(1, 1, At, B1); PG8_BAR; PG8_SCHED;
;     ...
;         if constexpr (ALIGN_EPI) { if (wr == 0) PG8_BAR; }
;         E(acc, cur, wr, wc, fr, fq);
	s_add_i32 s16, s34, s87
	v_lshl_add_u64 v[6:7], v[208:209], 0, s[24:25]
	s_mov_b32 m0, s16
	ds_read_b128 v[192:195], v216 offset:49152
	ds_read_b128 v[196:199], v216 offset:50176
	ds_read_b128 v[200:203], v216 offset:51200
	ds_read_b128 v[204:207], v216 offset:52224
	ds_read_b128 v[218:221], v216 offset:53248
	ds_read_b128 v[222:225], v216 offset:54272
	ds_read_b128 v[226:229], v216 offset:55296
	ds_read_b128 v[230:233], v216 offset:56320
	global_load_lds_dwordx4 v[6:7], off
	s_add_i32 m0, s16, 0x2000
	s_add_u32 s12, s12, 0x20080
	v_lshl_add_u64 v[6:7], v[234:235], 0, s[24:25]
	s_addc_u32 s13, s13, 0
	s_add_i32 s16, s35, s87
	global_load_lds_dwordx4 v[6:7], off
	v_lshl_add_u64 v[6:7], s[12:13], 0, v[158:159]
	s_mov_b32 m0, s16
	s_nop 0
	global_load_lds_dwordx4 v[6:7], off
	v_lshl_add_u64 v[6:7], s[12:13], 0, v[174:175]
	s_add_i32 m0, s16, 0x2000
	s_nop 0
	global_load_lds_dwordx4 v[6:7], off
	v_lshl_add_u64 v[6:7], v[236:237], 0, s[24:25]
	s_mov_b32 m0, s92
	s_nop 0
	global_load_lds_dwordx4 v[6:7], off
	v_lshl_add_u64 v[6:7], v[238:239], 0, s[24:25]
	s_mov_b32 m0, s93
	s_nop 0
	global_load_lds_dwordx4 v[6:7], off
	s_waitcnt vmcnt(8)
	s_waitcnt lgkmcnt(0)
	s_barrier
	s_setprio 1
	s_waitcnt lgkmcnt(0)
	v_mfma_f32_16x16x32_bf16 v[64:67], v[132:135], v[192:195], v[64:67]
	v_mfma_f32_16x16x32_bf16 v[60:63], v[140:143], v[192:195], v[60:63]
	v_mfma_f32_16x16x32_bf16 v[48:51], v[132:135], v[200:203], v[48:51]
	v_mfma_f32_16x16x32_bf16 v[44:47], v[140:143], v[200:203], v[44:47]
	v_mfma_f32_16x16x32_bf16 v[32:35], v[132:135], v[218:221], v[32:35]
	v_mfma_f32_16x16x32_bf16 v[28:31], v[140:143], v[218:221], v[28:31]
	v_mfma_f32_16x16x32_bf16 v[16:19], v[132:135], v[226:229], v[16:19]
	v_mfma_f32_16x16x32_bf16 v[12:15], v[140:143], v[226:229], v[12:15]
	v_mfma_f32_16x16x32_bf16 v[64:67], v[136:139], v[196:199], v[64:67]
	v_mfma_f32_16x16x32_bf16 v[60:63], v[144:147], v[196:199], v[60:63]
	v_mfma_f32_16x16x32_bf16 v[48:51], v[136:139], v[204:207], v[48:51]
	v_mfma_f32_16x16x32_bf16 v[44:47], v[144:147], v[204:207], v[44:47]
	v_mfma_f32_16x16x32_bf16 v[32:35], v[136:139], v[222:225], v[32:35]
	v_mfma_f32_16x16x32_bf16 v[28:31], v[144:147], v[222:225], v[28:31]
	v_mfma_f32_16x16x32_bf16 v[16:19], v[136:139], v[230:233], v[16:19]
	v_mfma_f32_16x16x32_bf16 v[12:15], v[144:147], v[230:233], v[12:15]
	v_mfma_f32_16x16x32_bf16 v[56:59], v[148:151], v[192:195], v[56:59]
	v_mfma_f32_16x16x32_bf16 v[52:55], v[184:187], v[192:195], v[52:55]
	v_mfma_f32_16x16x32_bf16 v[40:43], v[148:151], v[200:203], v[40:43]
	v_mfma_f32_16x16x32_bf16 v[36:39], v[184:187], v[200:203], v[36:39]
	v_mfma_f32_16x16x32_bf16 v[24:27], v[148:151], v[218:221], v[24:27]
	v_mfma_f32_16x16x32_bf16 v[20:23], v[184:187], v[218:221], v[20:23]
	v_mfma_f32_16x16x32_bf16 v[6:9], v[148:151], v[226:229], v[8:11]
	v_mfma_f32_16x16x32_bf16 v[2:5], v[184:187], v[226:229], v[2:5]
	v_mfma_f32_16x16x32_bf16 v[56:59], v[152:155], v[196:199], v[56:59]
	v_mfma_f32_16x16x32_bf16 v[52:55], v[188:191], v[196:199], v[52:55]
	v_mfma_f32_16x16x32_bf16 v[40:43], v[152:155], v[204:207], v[40:43]
	v_mfma_f32_16x16x32_bf16 v[36:39], v[188:191], v[204:207], v[36:39]
	v_mfma_f32_16x16x32_bf16 v[24:27], v[152:155], v[222:225], v[24:27]
	v_mfma_f32_16x16x32_bf16 v[20:23], v[188:191], v[222:225], v[20:23]
	v_mfma_f32_16x16x32_bf16 v[8:11], v[152:155], v[230:233], v[6:9]
	v_mfma_f32_16x16x32_bf16 v[4:7], v[188:191], v[230:233], v[2:5]
	s_setprio 0
	s_barrier
	s_add_i32 s21, s21, 2
	s_add_u32 s0, s0, 0x100
	s_addc_u32 s1, s1, 0
	s_add_u32 s18, s18, 0x100
	s_addc_u32 s19, s19, 0
	s_cmp_gt_u32 s21, 29
	s_cbranch_scc0 .LBB0_123
	s_and_b64 vcc, s[58:59], s[36:37]
	s_cbranch_vccz .LBB0_126
	s_barrier
	s_setprio 3

; #define PG8_BAR __builtin_amdgcn_s_barrier()
; template <class Epi, class SchedT, bool ALIGN_EPI, bool SP2>
; __device__ __forceinline__ void gemm_phase(LAS unsigned char* lds, const int ldk, const int nt, const SchedT& S, const Epi& E) {
;     ...
;         if (!has_next) break;
;         if (!(SchedT::kMode == 2 && cur.kind == 0)) {
; #pragma unroll
;         for (int a = 0; a < 2; ++a)
; #pragma unroll
;             for (int b = 0; b < 2; ++b)
; #pragma unroll
;                 for (int m = 0; m < 4; ++m)
; #pragma unroll
;                     for (int n = 0; n < 2; ++n) acc[a][b][m][n] = (f32x4){0.f, 0.f, 0.f, 0.f};
;         }
;         cur = nxt; cA = nA; cB = nB; ++ui;
;         if constexpr (ALIGN_EPI) { if (wr == 1) PG8_BAR; }
;     }
.LBB0_245:
.LBB0_246:
.LBB0_247:
.LBB0_249:
.LBB0_252:
.LBB0_253:
.LBB0_254:
.LBB0_256:
.LBB0_259:
.LBB0_260:
.LBB0_261:
.LBB0_263:
.LBB0_266:
.LBB0_267:
.LBB0_268:
.LBB0_270:
.LBB0_273:
.LBB0_274:
.LBB0_275:
.LBB0_277:
.LBB0_280:
.LBB0_281:
.LBB0_282:
.LBB0_284:
.LBB0_287:
.LBB0_288:
.LBB0_289:
.LBB0_291:
.LBB0_294:
.LBB0_295:
.LBB0_296:
.LBB0_298:
.LBB0_301:
.LBB0_302:
.LBB0_303:
.LBB0_305:
.LBB0_308:
.LBB0_309:
.LBB0_310:
.LBB0_312:
.LBB0_315:
.LBB0_316:
.LBB0_317:
.LBB0_319:
.LBB0_322:
.LBB0_323:
.LBB0_324:
.LBB0_326:
.LBB0_329:
.LBB0_330:
.LBB0_331:
.LBB0_333:
.LBB0_336:
.LBB0_337:
.LBB0_338:
.LBB0_340:
.LBB0_343:
.LBB0_344:
.LBB0_345:
.LBB0_347:
.LBB0_350:
.LBB0_351:
.LBB0_352:
.LBB0_354:
	s_and_b64 vcc, exec, s[36:37]
	s_mov_b64 s[0:1], -1
	s_cbranch_vccnz .LBB0_117
	s_branch .LBB0_116

; #define PG8_STAGE(bufoff, gbase, voff) do { _Pragma("unroll") for (int _i = 0; _i < 2; ++_i) \
;         __builtin_amdgcn_global_load_lds((const __attribute__((address_space(1))) unsigned*)((const char*)(gbase) + (voff)[_i]), (LAS unsigned*)(lds + (bufoff) + ldsw + _i * 8192), 16, 0, 0); } while (0)
; #define PG8_LDA(dst, b, h) do { _Pragma("unroll") for (int m = 0; m < 4; ++m) _Pragma("unroll") for (int k = 0; k < 2; ++k) dst[m][k] = *(const LAS bf16x8*)(lds + PG8_SA(b, h) + aoff + m * 2048 + k * 1024); } while (0)
; #define PG8_LDB(dst, b, h) do { _Pragma("unroll") for (int n = 0; n < 2; ++n) _Pragma("unroll") for (int k = 0; k < 2; ++k) dst[n][k] = *(const LAS bf16x8*)(lds + PG8_SB(b, h) + boff + n * 2048 + k * 1024); } while (0)
; #define PG8_MMA(ai, bj, At, Bt) do { __builtin_amdgcn_s_setprio(1); _Pragma("unroll") for (int m = 0; m < 4; ++m) _Pragma("unroll") for (int n = 0; n < 2; ++n) _Pragma("unroll") for (int k = 0; k < 2; ++k) \
;         acc[ai][bj][m][n] = __builtin_amdgcn_mfma_f32_16x16x32_bf16(Bt[n][k], At[m][k], acc[ai][bj][m][n], 0, 0, 0); __builtin_amdgcn_s_setprio(0); } while (0)
; #define PG8_WAIT_V(n) asm volatile("s_waitcnt vmcnt(" #n ")" ::: "memory")
; #define PG8_WAIT_L(n) asm volatile("s_waitcnt lgkmcnt(" #n ")" ::: "memory")
; #define PG8_BAR __builtin_amdgcn_s_barrier()
; #define PG8_SCHED __builtin_amdgcn_sched_barrier(0)
; template <class Epi, class SchedT, bool ALIGN_EPI, bool SP2>
; __device__ __forceinline__ void gemm_phase(LAS unsigned char* lds, const int ldk, const int nt, const SchedT& S, const Epi& E) {
;     ...
;             PG8_LDB(B0, 0, 0); PG8_LDB(B1, 0, 1); PG8_SCHED; PG8_LDA(At, 0, 0); PG8_STAGE(PG8_SA(1, 1), a1 + hstep, voffA);
;             PG8_WAIT_V(8); PG8_WAIT_L(0); PG8_BAR; PG8_MMA(0, 0, At, B0); PG8_MMA(0, 1, At, B1); PG8_BAR; PG8_SCHED;
;             PG8_LDA(At, 0, 1); PG8_STAGE(PG8_SB(0, 0), b2, voffB); PG8_STAGE(PG8_SB(0, 1), b2 + hstepB, voffB); PG8_STAGE(PG8_SA(0, 0), a2, voffA);
;             PG8_WAIT_V(8); PG8_WAIT_L(0); PG8_BAR; PG8_MMA(1, 0, At, B0); PG8_MMA(1, 1, At, B1); PG8_BAR; PG8_SCHED;
.LBB0_752:
	s_add_u32 s36, s34, 0xfff80080
	s_addc_u32 s37, s35, -1
	s_add_i32 s61, 0, 0x10000
	s_cmp_eq_u32 s59, 28
	s_cselect_b32 vcc_hi, s1, s37
	s_cselect_b32 vcc_lo, s0, s36
	s_cselect_b32 s37, s63, s17
	s_cselect_b32 s36, s62, s13
	s_add_i32 s64, 0, 0x14000
	v_add_u32_e32 v142, s61, v248
	v_add_u32_e32 v182, s64, v248
	ds_read_b128 v[130:133], v142
	ds_read_b128 v[134:137], v142 offset:1024
	ds_read_b128 v[138:141], v142 offset:2048
	ds_read_b128 v[142:145], v142 offset:3072
	ds_read_b128 v[158:161], v182
	ds_read_b128 v[174:177], v182 offset:1024
	ds_read_b128 v[178:181], v182 offset:2048
	ds_read_b128 v[182:185], v182 offset:3072
	v_lshl_add_u64 v[218:219], s[34:35], 0, v[154:155]
	s_add_i32 m0, s85, 0xc000
	ds_read_b128 v[186:189], v251
	ds_read_b128 v[190:193], v251 offset:1024
	ds_read_b128 v[194:197], v251 offset:2048
	ds_read_b128 v[198:201], v251 offset:3072
	ds_read_b128 v[202:205], v251 offset:4096
	ds_read_b128 v[206:209], v251 offset:5120
	ds_read_b128 v[210:213], v251 offset:6144
	ds_read_b128 v[214:217], v251 offset:7168
	global_load_lds_dwordx4 v[218:219], off
	v_lshl_add_u64 v[218:219], s[34:35], 0, v[156:157]
	s_add_i32 m0, s85, 0xe000
	s_nop 0
	global_load_lds_dwordx4 v[218:219], off
	s_waitcnt vmcnt(8)
	s_waitcnt lgkmcnt(0)
	s_barrier
	s_setprio 1
	s_waitcnt lgkmcnt(0)
	v_mfma_f32_16x16x32_bf16 v[126:129], v[130:133], v[186:189], v[126:129]
	v_mfma_f32_16x16x32_bf16 v[62:65], v[138:141], v[186:189], v[62:65]
	v_mfma_f32_16x16x32_bf16 v[118:121], v[130:133], v[194:197], v[118:121]
	v_mfma_f32_16x16x32_bf16 v[58:61], v[138:141], v[194:197], v[58:61]
	v_mfma_f32_16x16x32_bf16 v[110:113], v[130:133], v[202:205], v[110:113]
	v_mfma_f32_16x16x32_bf16 v[46:49], v[138:141], v[202:205], v[46:49]
	v_mfma_f32_16x16x32_bf16 v[106:109], v[130:133], v[210:213], v[106:109]
	v_mfma_f32_16x16x32_bf16 v[42:45], v[138:141], v[210:213], v[42:45]
	v_mfma_f32_16x16x32_bf16 v[126:129], v[134:137], v[190:193], v[126:129]
	v_mfma_f32_16x16x32_bf16 v[62:65], v[142:145], v[190:193], v[62:65]
	v_mfma_f32_16x16x32_bf16 v[118:121], v[134:137], v[198:201], v[118:121]
	v_mfma_f32_16x16x32_bf16 v[58:61], v[142:145], v[198:201], v[58:61]
	v_mfma_f32_16x16x32_bf16 v[110:113], v[134:137], v[206:209], v[110:113]
	v_mfma_f32_16x16x32_bf16 v[46:49], v[142:145], v[206:209], v[46:49]
	v_mfma_f32_16x16x32_bf16 v[106:109], v[134:137], v[214:217], v[106:109]
	v_mfma_f32_16x16x32_bf16 v[42:45], v[142:145], v[214:217], v[42:45]
	v_mfma_f32_16x16x32_bf16 v[122:125], v[158:161], v[186:189], v[122:125]
	v_mfma_f32_16x16x32_bf16 v[54:57], v[178:181], v[186:189], v[54:57]
	v_mfma_f32_16x16x32_bf16 v[114:117], v[158:161], v[194:197], v[114:117]
	v_mfma_f32_16x16x32_bf16 v[50:53], v[178:181], v[194:197], v[50:53]
	v_mfma_f32_16x16x32_bf16 v[102:105], v[158:161], v[202:205], v[102:105]
	v_mfma_f32_16x16x32_bf16 v[38:41], v[178:181], v[202:205], v[38:41]
	v_mfma_f32_16x16x32_bf16 v[98:101], v[158:161], v[210:213], v[98:101]
	v_mfma_f32_16x16x32_bf16 v[34:37], v[178:181], v[210:213], v[34:37]
	v_mfma_f32_16x16x32_bf16 v[122:125], v[174:177], v[190:193], v[122:125]
	v_mfma_f32_16x16x32_bf16 v[54:57], v[182:185], v[190:193], v[54:57]
	v_mfma_f32_16x16x32_bf16 v[114:117], v[174:177], v[198:201], v[114:117]
	v_mfma_f32_16x16x32_bf16 v[50:53], v[182:185], v[198:201], v[50:53]
	v_mfma_f32_16x16x32_bf16 v[102:105], v[174:177], v[206:209], v[102:105]
	v_mfma_f32_16x16x32_bf16 v[38:41], v[182:185], v[206:209], v[38:41]
	v_mfma_f32_16x16x32_bf16 v[98:101], v[174:177], v[214:217], v[98:101]
	v_mfma_f32_16x16x32_bf16 v[34:37], v[182:185], v[214:217], v[34:37]
	s_setprio 0
	s_barrier
	s_add_i32 s61, s61, s84
	v_lshl_add_u64 v[218:219], s[36:37], 0, v[0:1]
	s_mov_b32 m0, s61
	ds_read_b128 v[186:189], v251 offset:16384
	ds_read_b128 v[190:193], v251 offset:17408
	ds_read_b128 v[194:197], v251 offset:18432
	ds_read_b128 v[198:201], v251 offset:19456
	ds_read_b128 v[202:205], v251 offset:20480
	ds_read_b128 v[206:209], v251 offset:21504
	ds_read_b128 v[210:213], v251 offset:22528
	ds_read_b128 v[214:217], v251 offset:23552
	global_load_lds_dwordx4 v[218:219], off
	s_add_i32 m0, s61, 0x2000
	s_add_u32 s94, s36, 0x20000
	v_lshl_add_u64 v[220:221], s[36:37], 0, v[150:151]
	s_addc_u32 s95, s37, 0
	s_add_i32 s61, s64, s84
	global_load_lds_dwordx4 v[220:221], off
	v_lshl_add_u64 v[222:223], s[94:95], 0, v[0:1]
	s_mov_b32 m0, s61
	v_lshl_add_u64 v[224:225], vcc, 0, v[148:149]
	global_load_lds_dwordx4 v[222:223], off
	v_lshl_add_u64 v[222:223], s[94:95], 0, v[150:151]
	s_add_i32 m0, s61, 0x2000
	s_nop 0
	global_load_lds_dwordx4 v[222:223], off
	v_lshl_add_u64 v[222:223], vcc, 0, v[146:147]
	s_mov_b32 m0, s85
	s_nop 0
	global_load_lds_dwordx4 v[222:223], off
	s_mov_b32 m0, s86
	s_nop 0
	global_load_lds_dwordx4 v[224:225], off
	s_waitcnt vmcnt(8)
	s_waitcnt lgkmcnt(0)
	s_barrier
; #define PG8_STAGE(bufoff, gbase, voff) do { _Pragma("unroll") for (int _i = 0; _i < 2; ++_i) \
;         __builtin_amdgcn_global_load_lds((const __attribute__((address_space(1))) unsigned*)((const char*)(gbase) + (voff)[_i]), (LAS unsigned*)(lds + (bufoff) + ldsw + _i * 8192), 16, 0, 0); } while (0)
; #define PG8_LDA(dst, b, h) do { _Pragma("unroll") for (int m = 0; m < 4; ++m) _Pragma("unroll") for (int k = 0; k < 2; ++k) dst[m][k] = *(const LAS bf16x8*)(lds + PG8_SA(b, h) + aoff + m * 2048 + k * 1024); } while (0)
; #define PG8_LDB(dst, b, h) do { _Pragma("unroll") for (int n = 0; n < 2; ++n) _Pragma("unroll") for (int k = 0; k < 2; ++k) dst[n][k] = *(const LAS bf16x8*)(lds + PG8_SB(b, h) + boff + n * 2048 + k * 1024); } while (0)
; #define PG8_MMA(ai, bj, At, Bt) do { __builtin_amdgcn_s_setprio(1); _Pragma("unroll") for (int m = 0; m < 4; ++m) _Pragma("unroll") for (int n = 0; n < 2; ++n) _Pragma("unroll") for (int k = 0; k < 2; ++k) \
;         acc[ai][bj][m][n] = __builtin_amdgcn_mfma_f32_16x16x32_bf16(Bt[n][k], At[m][k], acc[ai][bj][m][n], 0, 0, 0); __builtin_amdgcn_s_setprio(0); } while (0)
; #define PG8_WAIT_V(n) asm volatile("s_waitcnt vmcnt(" #n ")" ::: "memory")
; #define PG8_WAIT_L(n) asm volatile("s_waitcnt lgkmcnt(" #n ")" ::: "memory")
; #define PG8_BAR __builtin_amdgcn_s_barrier()
; #define PG8_SCHED __builtin_amdgcn_sched_barrier(0)
; template <class Epi, class SchedT, bool ALIGN_EPI, bool SP2>
; __device__ __forceinline__ void gemm_phase(LAS unsigned char* lds, const int ldk, const int nt, const SchedT& S, const Epi& E) {
;     ...
;             PG8_WAIT_V(8); PG8_WAIT_L(0); PG8_BAR; PG8_MMA(1, 0, At, B0); PG8_MMA(1, 1, At, B1); PG8_BAR; PG8_SCHED;
;             PG8_LDB(B0, 1, 0); PG8_LDB(B1, 1, 1); PG8_SCHED; PG8_LDA(At, 1, 0); PG8_STAGE(PG8_SA(0, 1), a2 + hstep, voffA);
;             PG8_WAIT_V(8); PG8_WAIT_L(0); PG8_BAR; PG8_MMA(0, 0, At, B0); PG8_MMA(0, 1, At, B1); PG8_BAR; PG8_SCHED;
	s_setprio 1
	s_waitcnt lgkmcnt(0)
	v_mfma_f32_16x16x32_bf16 v[94:97], v[130:133], v[186:189], v[94:97]
	v_mfma_f32_16x16x32_bf16 v[30:33], v[138:141], v[186:189], v[30:33]
	v_mfma_f32_16x16x32_bf16 v[90:93], v[130:133], v[194:197], v[90:93]
	v_mfma_f32_16x16x32_bf16 v[26:29], v[138:141], v[194:197], v[26:29]
	v_mfma_f32_16x16x32_bf16 v[78:81], v[130:133], v[202:205], v[78:81]
	v_mfma_f32_16x16x32_bf16 v[14:17], v[138:141], v[202:205], v[14:17]
	v_mfma_f32_16x16x32_bf16 v[74:77], v[130:133], v[210:213], v[74:77]
	v_mfma_f32_16x16x32_bf16 v[10:13], v[138:141], v[210:213], v[10:13]
	v_mfma_f32_16x16x32_bf16 v[94:97], v[134:137], v[190:193], v[94:97]
	v_mfma_f32_16x16x32_bf16 v[30:33], v[142:145], v[190:193], v[30:33]
	v_mfma_f32_16x16x32_bf16 v[90:93], v[134:137], v[198:201], v[90:93]
	v_mfma_f32_16x16x32_bf16 v[26:29], v[142:145], v[198:201], v[26:29]
	v_mfma_f32_16x16x32_bf16 v[78:81], v[134:137], v[206:209], v[78:81]
	v_mfma_f32_16x16x32_bf16 v[14:17], v[142:145], v[206:209], v[14:17]
	v_mfma_f32_16x16x32_bf16 v[74:77], v[134:137], v[214:217], v[74:77]
	v_mfma_f32_16x16x32_bf16 v[10:13], v[142:145], v[214:217], v[10:13]
	v_mfma_f32_16x16x32_bf16 v[86:89], v[158:161], v[186:189], v[86:89]
	v_mfma_f32_16x16x32_bf16 v[22:25], v[178:181], v[186:189], v[22:25]
	v_mfma_f32_16x16x32_bf16 v[82:85], v[158:161], v[194:197], v[82:85]
	v_mfma_f32_16x16x32_bf16 v[18:21], v[178:181], v[194:197], v[18:21]
	v_mfma_f32_16x16x32_bf16 v[70:73], v[158:161], v[202:205], v[70:73]
	v_mfma_f32_16x16x32_bf16 v[6:9], v[178:181], v[202:205], v[6:9]
	v_mfma_f32_16x16x32_bf16 v[66:69], v[158:161], v[210:213], v[66:69]
	v_mfma_f32_16x16x32_bf16 v[2:5], v[178:181], v[210:213], v[2:5]
	v_mfma_f32_16x16x32_bf16 v[86:89], v[174:177], v[190:193], v[86:89]
	v_mfma_f32_16x16x32_bf16 v[22:25], v[182:185], v[190:193], v[22:25]
	v_mfma_f32_16x16x32_bf16 v[82:85], v[174:177], v[198:201], v[82:85]
	v_mfma_f32_16x16x32_bf16 v[18:21], v[182:185], v[198:201], v[18:21]
	v_mfma_f32_16x16x32_bf16 v[70:73], v[174:177], v[206:209], v[70:73]
	v_mfma_f32_16x16x32_bf16 v[6:9], v[182:185], v[206:209], v[6:9]
	v_mfma_f32_16x16x32_bf16 v[66:69], v[174:177], v[214:217], v[66:69]
	v_mfma_f32_16x16x32_bf16 v[2:5], v[182:185], v[214:217], v[2:5]
	s_setprio 0
	s_barrier
	s_add_i32 s61, 0, 0x18000
	s_add_i32 s64, 0, 0x1c000
	v_add_u32_e32 v142, s61, v248
	v_add_u32_e32 v182, s64, v248
	ds_read_b128 v[130:133], v142
	ds_read_b128 v[134:137], v142 offset:1024
	ds_read_b128 v[138:141], v142 offset:2048
	ds_read_b128 v[142:145], v142 offset:3072
	ds_read_b128 v[158:161], v182
	ds_read_b128 v[174:177], v182 offset:1024
	ds_read_b128 v[178:181], v182 offset:2048
	ds_read_b128 v[182:185], v182 offset:3072
	s_add_u32 s94, vcc_lo, 0x80000
	s_addc_u32 s95, vcc_hi, 0
	s_mov_b32 m0, s87
	v_lshl_add_u64 v[226:227], s[94:95], 0, v[146:147]
	ds_read_b128 v[186:189], v251 offset:32768
	ds_read_b128 v[190:193], v251 offset:33792
	ds_read_b128 v[194:197], v251 offset:34816
	ds_read_b128 v[198:201], v251 offset:35840
	ds_read_b128 v[202:205], v251 offset:36864
	ds_read_b128 v[206:209], v251 offset:37888
	ds_read_b128 v[210:213], v251 offset:38912
	ds_read_b128 v[214:217], v251 offset:39936
	global_load_lds_dwordx4 v[226:227], off
	v_lshl_add_u64 v[226:227], s[94:95], 0, v[148:149]
	s_mov_b32 m0, s88
	s_nop 0
	global_load_lds_dwordx4 v[226:227], off
	s_waitcnt vmcnt(8)
	s_waitcnt lgkmcnt(0)
	s_barrier
	s_setprio 1
	s_waitcnt lgkmcnt(0)
	v_mfma_f32_16x16x32_bf16 v[126:129], v[130:133], v[186:189], v[126:129]
	v_mfma_f32_16x16x32_bf16 v[62:65], v[138:141], v[186:189], v[62:65]
	v_mfma_f32_16x16x32_bf16 v[118:121], v[130:133], v[194:197], v[118:121]
	v_mfma_f32_16x16x32_bf16 v[58:61], v[138:141], v[194:197], v[58:61]
	v_mfma_f32_16x16x32_bf16 v[110:113], v[130:133], v[202:205], v[110:113]
	v_mfma_f32_16x16x32_bf16 v[46:49], v[138:141], v[202:205], v[46:49]
	v_mfma_f32_16x16x32_bf16 v[106:109], v[130:133], v[210:213], v[106:109]
	v_mfma_f32_16x16x32_bf16 v[42:45], v[138:141], v[210:213], v[42:45]
	v_mfma_f32_16x16x32_bf16 v[126:129], v[134:137], v[190:193], v[126:129]
	v_mfma_f32_16x16x32_bf16 v[62:65], v[142:145], v[190:193], v[62:65]
	v_mfma_f32_16x16x32_bf16 v[118:121], v[134:137], v[198:201], v[118:121]
	v_mfma_f32_16x16x32_bf16 v[58:61], v[142:145], v[198:201], v[58:61]
	v_mfma_f32_16x16x32_bf16 v[110:113], v[134:137], v[206:209], v[110:113]
	v_mfma_f32_16x16x32_bf16 v[46:49], v[142:145], v[206:209], v[46:49]
	v_mfma_f32_16x16x32_bf16 v[106:109], v[134:137], v[214:217], v[106:109]
	v_mfma_f32_16x16x32_bf16 v[42:45], v[142:145], v[214:217], v[42:45]
	v_mfma_f32_16x16x32_bf16 v[122:125], v[158:161], v[186:189], v[122:125]
	v_mfma_f32_16x16x32_bf16 v[54:57], v[178:181], v[186:189], v[54:57]
	v_mfma_f32_16x16x32_bf16 v[114:117], v[158:161], v[194:197], v[114:117]
	v_mfma_f32_16x16x32_bf16 v[50:53], v[178:181], v[194:197], v[50:53]
	v_mfma_f32_16x16x32_bf16 v[102:105], v[158:161], v[202:205], v[102:105]
	v_mfma_f32_16x16x32_bf16 v[38:41], v[178:181], v[202:205], v[38:41]
	v_mfma_f32_16x16x32_bf16 v[98:101], v[158:161], v[210:213], v[98:101]
	v_mfma_f32_16x16x32_bf16 v[34:37], v[178:181], v[210:213], v[34:37]
	v_mfma_f32_16x16x32_bf16 v[122:125], v[174:177], v[190:193], v[122:125]
	v_mfma_f32_16x16x32_bf16 v[54:57], v[182:185], v[190:193], v[54:57]
	v_mfma_f32_16x16x32_bf16 v[114:117], v[174:177], v[198:201], v[114:117]
	v_mfma_f32_16x16x32_bf16 v[50:53], v[182:185], v[198:201], v[50:53]
	v_mfma_f32_16x16x32_bf16 v[102:105], v[174:177], v[206:209], v[102:105]
	v_mfma_f32_16x16x32_bf16 v[38:41], v[182:185], v[206:209], v[38:41]
	v_mfma_f32_16x16x32_bf16 v[98:101], v[174:177], v[214:217], v[98:101]
	v_mfma_f32_16x16x32_bf16 v[34:37], v[182:185], v[214:217], v[34:37]
	s_setprio 0
	s_barrier
; #define PG8_LDA(dst, b, h) do { _Pragma("unroll") for (int m = 0; m < 4; ++m) _Pragma("unroll") for (int k = 0; k < 2; ++k) dst[m][k] = *(const LAS bf16x8*)(lds + PG8_SA(b, h) + aoff + m * 2048 + k * 1024); } while (0)
; __device__ __forceinline__ float row_rstd(const float* ssp, int row, int fq) {
;     const f32x4 a = *(const f32x4*)(ssp + (size_t)row * 32 + 8 * fq), b = *(const f32x4*)(ssp + (size_t)row * 32 + 8 * fq + 4);
;     float s = ((a[0] + a[1]) + (a[2] + a[3])) + ((b[0] + b[1]) + (b[2] + b[3]));
;     s += __shfl_xor(s, 16); s += __shfl_xor(s, 32);
; template <class Epi, class SchedT, bool ALIGN_EPI, bool SP2>
; __device__ __forceinline__ void gemm_phase(LAS unsigned char* lds, const int ldk, const int nt, const SchedT& S, const Epi& E) {
;     ...
;             PG8_LDA(At, 1, 1); PG8_STAGE(PG8_SB(1, 0), b3, voffB); PG8_STAGE(PG8_SB(1, 1), b3 + hstepB, voffB); PG8_STAGE(PG8_SA(1, 0), a3, voffA);
;             PG8_WAIT_V(8); PG8_WAIT_L(0); PG8_BAR; PG8_MMA(1, 0, At, B0); PG8_MMA(1, 1, At, B1); PG8_BAR; PG8_SCHED;
;             } else {
;             PG8_LDB(B0, 0, 0); PG8_SCHED; PG8_LDA(At, 0, 0); PG8_STAGE(PG8_SA(1, 1), a1 + hstep, voffA);
;             PG8_WAIT_L(8); PG8_BAR; PG8_WAIT_L(0); PG8_MMA(0, 0, At, B0); PG8_BAR; PG8_SCHED;
;             PG8_LDB(B1, 0, 1); PG8_STAGE(PG8_SB(0, 0), b2, voffB);
;             PG8_BAR; PG8_WAIT_L(0); PG8_MMA(0, 1, At, B1); PG8_BAR;
;             PG8_LDA(At, 0, 1); PG8_STAGE(PG8_SA(0, 0), a2, voffA);
;             PG8_BAR; PG8_WAIT_L(0); PG8_MMA(1, 0, At, B0); PG8_BAR; PG8_SCHED;
;             PG8_STAGE(PG8_SB(0, 1), b2 + hstepB, voffB);
;             PG8_WAIT_V(6); PG8_BAR; PG8_MMA(1, 1, At, B1); PG8_BAR;
;             PG8_LDB(B0, 1, 0); PG8_SCHED; PG8_LDA(At, 1, 0); PG8_STAGE(PG8_SA(0, 1), a2 + hstep, voffA);
;             PG8_WAIT_L(8); PG8_BAR; PG8_WAIT_L(0); PG8_MMA(0, 0, At, B0); PG8_BAR; PG8_SCHED;
;             PG8_LDB(B1, 1, 1); PG8_STAGE(PG8_SB(1, 0), b3, voffB);
;             PG8_BAR; PG8_WAIT_L(0); PG8_MMA(0, 1, At, B1); PG8_BAR;
;             PG8_LDA(At, 1, 1); PG8_STAGE(PG8_SA(1, 0), a3, voffA);
;             PG8_BAR; PG8_WAIT_L(0); PG8_MMA(1, 0, At, B0); PG8_BAR; PG8_SCHED;
;             PG8_STAGE(PG8_SB(1, 1), b3 + hstepB, voffB);
;             PG8_WAIT_V(6); PG8_BAR; PG8_MMA(1, 1, At, B1); PG8_BAR;
;             }
;         }
;         if constexpr (ALIGN_EPI) { if (wr == 0) PG8_BAR; }
	s_add_i32 s61, s61, s84
	v_lshl_add_u64 v[218:219], v[218:219], 0, s[24:25]
	s_mov_b32 m0, s61
	ds_read_b128 v[186:189], v251 offset:49152
	ds_read_b128 v[190:193], v251 offset:50176
	ds_read_b128 v[194:197], v251 offset:51200
	ds_read_b128 v[198:201], v251 offset:52224
	ds_read_b128 v[202:205], v251 offset:53248
	ds_read_b128 v[206:209], v251 offset:54272
	ds_read_b128 v[210:213], v251 offset:55296
	ds_read_b128 v[214:217], v251 offset:56320
	global_load_lds_dwordx4 v[218:219], off
	s_add_i32 m0, s61, 0x2000
	s_add_u32 s36, s36, 0x20080
	v_lshl_add_u64 v[218:219], v[220:221], 0, s[24:25]
	s_addc_u32 s37, s37, 0
	s_add_i32 s61, s64, s84
	global_load_lds_dwordx4 v[218:219], off
	v_lshl_add_u64 v[218:219], s[36:37], 0, v[0:1]
	s_mov_b32 m0, s61
	s_nop 0
	global_load_lds_dwordx4 v[218:219], off
	v_lshl_add_u64 v[218:219], s[36:37], 0, v[150:151]
	s_add_i32 m0, s61, 0x2000
	s_nop 0
	global_load_lds_dwordx4 v[218:219], off
	v_lshl_add_u64 v[218:219], v[222:223], 0, s[24:25]
	s_mov_b32 m0, s89
	s_nop 0
	global_load_lds_dwordx4 v[218:219], off
	v_lshl_add_u64 v[218:219], v[224:225], 0, s[24:25]
	s_mov_b32 m0, s90
	s_nop 0
	global_load_lds_dwordx4 v[218:219], off
	s_waitcnt vmcnt(8)
	s_waitcnt lgkmcnt(0)
	s_barrier
	s_setprio 1
	s_waitcnt lgkmcnt(0)
	v_mfma_f32_16x16x32_bf16 v[94:97], v[130:133], v[186:189], v[94:97]
	v_mfma_f32_16x16x32_bf16 v[30:33], v[138:141], v[186:189], v[30:33]
	v_mfma_f32_16x16x32_bf16 v[90:93], v[130:133], v[194:197], v[90:93]
	v_mfma_f32_16x16x32_bf16 v[26:29], v[138:141], v[194:197], v[26:29]
	v_mfma_f32_16x16x32_bf16 v[78:81], v[130:133], v[202:205], v[78:81]
	v_mfma_f32_16x16x32_bf16 v[14:17], v[138:141], v[202:205], v[14:17]
	v_mfma_f32_16x16x32_bf16 v[74:77], v[130:133], v[210:213], v[74:77]
	v_mfma_f32_16x16x32_bf16 v[10:13], v[138:141], v[210:213], v[10:13]
	v_mfma_f32_16x16x32_bf16 v[94:97], v[134:137], v[190:193], v[94:97]
	v_mfma_f32_16x16x32_bf16 v[30:33], v[142:145], v[190:193], v[30:33]
	v_mfma_f32_16x16x32_bf16 v[90:93], v[134:137], v[198:201], v[90:93]
	v_mfma_f32_16x16x32_bf16 v[26:29], v[142:145], v[198:201], v[26:29]
	v_mfma_f32_16x16x32_bf16 v[78:81], v[134:137], v[206:209], v[78:81]
	v_mfma_f32_16x16x32_bf16 v[14:17], v[142:145], v[206:209], v[14:17]
	v_mfma_f32_16x16x32_bf16 v[74:77], v[134:137], v[214:217], v[74:77]
	v_mfma_f32_16x16x32_bf16 v[10:13], v[142:145], v[214:217], v[10:13]
	v_mfma_f32_16x16x32_bf16 v[86:89], v[158:161], v[186:189], v[86:89]
	v_mfma_f32_16x16x32_bf16 v[22:25], v[178:181], v[186:189], v[22:25]
	v_mfma_f32_16x16x32_bf16 v[82:85], v[158:161], v[194:197], v[82:85]
	v_mfma_f32_16x16x32_bf16 v[18:21], v[178:181], v[194:197], v[18:21]
	v_mfma_f32_16x16x32_bf16 v[70:73], v[158:161], v[202:205], v[70:73]
	v_mfma_f32_16x16x32_bf16 v[6:9], v[178:181], v[202:205], v[6:9]
	v_mfma_f32_16x16x32_bf16 v[66:69], v[158:161], v[210:213], v[66:69]
	v_mfma_f32_16x16x32_bf16 v[2:5], v[178:181], v[210:213], v[2:5]
	v_mfma_f32_16x16x32_bf16 v[86:89], v[174:177], v[190:193], v[86:89]
	v_mfma_f32_16x16x32_bf16 v[22:25], v[182:185], v[190:193], v[22:25]
	v_mfma_f32_16x16x32_bf16 v[82:85], v[174:177], v[198:201], v[82:85]
	v_mfma_f32_16x16x32_bf16 v[18:21], v[182:185], v[198:201], v[18:21]
	v_mfma_f32_16x16x32_bf16 v[70:73], v[174:177], v[206:209], v[70:73]
	v_mfma_f32_16x16x32_bf16 v[6:9], v[182:185], v[206:209], v[6:9]
	v_mfma_f32_16x16x32_bf16 v[66:69], v[174:177], v[214:217], v[66:69]
	v_mfma_f32_16x16x32_bf16 v[2:5], v[182:185], v[214:217], v[2:5]
	s_setprio 0
	s_barrier
	s_add_i32 s59, s59, 2
	s_add_u32 s34, s34, 0x100
	s_addc_u32 s35, s35, 0
	s_add_u32 s13, s13, 0x100
	s_addc_u32 s17, s17, 0
	s_cmp_gt_u32 s59, 29
	s_cbranch_scc0 .LBB0_752
	v_lshl_add_u32 v130, s12, 8, v247
	v_lshlrev_b32_e32 v140, 7, v130
	v_mov_b32_e32 v141, 0
	v_lshl_add_u64 v[132:133], v[152:153], 0, v[140:141]
	v_add_u32_e32 v140, 0x1000, v140
	v_lshl_add_u64 v[134:135], v[152:153], 0, v[140:141]
	v_add_u32_e32 v140, 0x3000, v140
	v_lshl_add_u64 v[136:137], v[152:153], 0, v[140:141]
	v_add_u32_e32 v140, 0x1000, v140
	v_lshl_add_u64 v[138:139], v[152:153], 0, v[140:141]
	global_load_dwordx4 v[174:177], v[132:133], off
	global_load_dwordx4 v[178:181], v[132:133], off offset:16
	global_load_dwordx4 v[182:185], v[132:133], off offset:2048
	global_load_dwordx4 v[186:189], v[132:133], off offset:2064
	global_load_dwordx4 v[190:193], v[134:135], off
	global_load_dwordx4 v[194:197], v[134:135], off offset:16
	global_load_dwordx4 v[198:201], v[134:135], off offset:2048
	global_load_dwordx4 v[202:205], v[134:135], off offset:2064
	global_load_dwordx4 v[206:209], v[136:137], off
	global_load_dwordx4 v[210:213], v[136:137], off offset:16
	global_load_dwordx4 v[214:217], v[136:137], off offset:2048
	global_load_dwordx4 v[218:221], v[136:137], off offset:2064
	global_load_dwordx4 v[222:225], v[138:139], off
	global_load_dwordx4 v[226:229], v[138:139], off offset:16
	global_load_dwordx4 v[230:233], v[138:139], off offset:2048
	global_load_dwordx4 v[234:237], v[138:139], off offset:2064
	v_xor_b32_e32 v238, 16, v241
	v_xor_b32_e32 v239, 32, v241
	v_lshlrev_b32_e32 v238, 2, v238
	v_lshlrev_b32_e32 v239, 2, v239
	s_and_b64 vcc, s[56:57], s[50:51]
	s_cbranch_vccz .LBB0_755
	s_barrier
	s_setprio 3
; __device__ __forceinline__ float row_rstd(const float* ssp, int row, int fq) {
;     const f32x4 a = *(const f32x4*)(ssp + (size_t)row * 32 + 8 * fq), b = *(const f32x4*)(ssp + (size_t)row * 32 + 8 * fq + 4);
;     float s = ((a[0] + a[1]) + (a[2] + a[3])) + ((b[0] + b[1]) + (b[2] + b[3]));
;     s += __shfl_xor(s, 16); s += __shfl_xor(s, 32);
;     return __builtin_amdgcn_rsqf(s * (1.0f / 2048.0f) + 1e-6f);
;     __device__ __forceinline__ void operator()(f32x4 (&acc)[2][2][4][2], const Unit& u, int wr, int wc, int fr, int fq) const {
;         const int row0 = u.pm * BM + wr * 64 + fr;
; #pragma unroll
;         for (int ai = 0; ai < 2; ++ai)
; #pragma unroll
;             for (int m = 0; m < 4; ++m) { const float rstd = row_rstd(ss, row0 + ai * HALF + m * 16, fq);
; #pragma unroll
;                 for (int bj = 0; bj < 2; ++bj) { acc[ai][bj][m][0] *= rstd; acc[ai][bj][m][1] *= rstd; } }
; #pragma unroll
;         for (int n = 0; n < 2; ++n) {
;             const int j4 = u.pn * 128 + wc * 32 + 8 * fq + 4 * n;
;             f32x4 kc[2][3], bc[2];
; #pragma unroll
;             for (int bj = 0; bj < 2; ++bj) { bc[bj] = *(const f32x4*)(cb + bj * FF + j4);
; #pragma unroll
;                 for (int w = 0; w < 3; ++w) kc[bj][w] = *(const f32x4*)(ck + w * NUP + bj * FF + j4); }
.LBB0_755:
	s_waitcnt vmcnt(14)
	v_add_f32_e32 v174, v174, v175
	v_add_f32_e32 v176, v176, v177
	v_add_f32_e32 v178, v178, v179
	v_add_f32_e32 v180, v180, v181
	v_add_f32_e32 v174, v174, v176
	v_add_f32_e32 v178, v178, v180
	v_add_f32_e32 v130, v174, v178
	s_waitcnt vmcnt(12)
	v_add_f32_e32 v182, v182, v183
	v_add_f32_e32 v184, v184, v185
	v_add_f32_e32 v186, v186, v187
	v_add_f32_e32 v188, v188, v189
	v_add_f32_e32 v182, v182, v184
	v_add_f32_e32 v186, v186, v188
	v_add_f32_e32 v132, v182, v186
	s_waitcnt vmcnt(10)
	v_add_f32_e32 v190, v190, v191
	v_add_f32_e32 v192, v192, v193
	v_add_f32_e32 v194, v194, v195
	v_add_f32_e32 v196, v196, v197
	v_add_f32_e32 v190, v190, v192
	v_add_f32_e32 v194, v194, v196
	v_add_f32_e32 v134, v190, v194
	s_waitcnt vmcnt(8)
	v_add_f32_e32 v198, v198, v199
	v_add_f32_e32 v200, v200, v201
	v_add_f32_e32 v202, v202, v203
	v_add_f32_e32 v204, v204, v205
	v_add_f32_e32 v198, v198, v200
	v_add_f32_e32 v202, v202, v204
	v_add_f32_e32 v136, v198, v202
	s_waitcnt vmcnt(6)
	v_add_f32_e32 v206, v206, v207
	v_add_f32_e32 v208, v208, v209
	v_add_f32_e32 v210, v210, v211
	v_add_f32_e32 v212, v212, v213
	v_add_f32_e32 v206, v206, v208
	v_add_f32_e32 v210, v210, v212
	v_add_f32_e32 v138, v206, v210
	s_waitcnt vmcnt(4)
	v_add_f32_e32 v214, v214, v215
	v_add_f32_e32 v216, v216, v217
	v_add_f32_e32 v218, v218, v219
	v_add_f32_e32 v220, v220, v221
	v_add_f32_e32 v214, v214, v216
	v_add_f32_e32 v218, v218, v220
	v_add_f32_e32 v140, v214, v218
	s_waitcnt vmcnt(2)
	v_add_f32_e32 v222, v222, v223
	v_add_f32_e32 v224, v224, v225
	v_add_f32_e32 v226, v226, v227
	v_add_f32_e32 v228, v228, v229
	v_add_f32_e32 v222, v222, v224
	v_add_f32_e32 v226, v226, v228
	v_add_f32_e32 v142, v222, v226
	s_waitcnt vmcnt(0)
	v_add_f32_e32 v230, v230, v231
	v_add_f32_e32 v232, v232, v233
	v_add_f32_e32 v234, v234, v235
	v_add_f32_e32 v236, v236, v237
	v_add_f32_e32 v230, v230, v232
	v_add_f32_e32 v234, v234, v236
	v_add_f32_e32 v144, v230, v234
	v_lshl_or_b32 v242, s16, 7, v250
	v_lshlrev_b32_e32 v252, 1, v242
	v_lshlrev_b32_e32 v242, 2, v242
	v_add_u32_e32 v131, 0x5600, v242
	v_add_u32_e32 v133, 0xac00, v242
	v_add_u32_e32 v135, 0x10200, v242
	v_add_u32_e32 v137, 0x15800, v242
	v_add_u32_e32 v139, 0x1ae00, v242
	global_load_dwordx4 v[182:185], v242, s[18:19]
	global_load_dwordx4 v[186:189], v133, s[18:19]
	global_load_dwordx4 v[190:193], v137, s[18:19]
	global_load_dwordx4 v[194:197], v242, s[20:21]
	global_load_dwordx4 v[198:201], v131, s[18:19]
	global_load_dwordx4 v[202:205], v135, s[18:19]
	global_load_dwordx4 v[206:209], v139, s[18:19]
	global_load_dwordx4 v[210:213], v131, s[20:21]
	ds_bpermute_b32 v174, v238, v130
	ds_bpermute_b32 v175, v238, v132
	ds_bpermute_b32 v176, v238, v134
	ds_bpermute_b32 v177, v238, v136
	ds_bpermute_b32 v178, v238, v138
	ds_bpermute_b32 v179, v238, v140
	ds_bpermute_b32 v180, v238, v142
	ds_bpermute_b32 v181, v238, v144
	s_waitcnt lgkmcnt(0)
	v_add_f32_e32 v130, v130, v174
	v_add_f32_e32 v132, v132, v175
	v_add_f32_e32 v134, v134, v176
	v_add_f32_e32 v136, v136, v177
	v_add_f32_e32 v138, v138, v178
	v_add_f32_e32 v140, v140, v179
	v_add_f32_e32 v142, v142, v180
	v_add_f32_e32 v144, v144, v181
	ds_bpermute_b32 v174, v239, v130
	ds_bpermute_b32 v175, v239, v132
	ds_bpermute_b32 v176, v239, v134
	ds_bpermute_b32 v177, v239, v136
	ds_bpermute_b32 v178, v239, v138
	ds_bpermute_b32 v179, v239, v140
	ds_bpermute_b32 v180, v239, v142
	ds_bpermute_b32 v181, v239, v144
	s_waitcnt lgkmcnt(0)
	v_add_f32_e32 v130, v130, v174
	v_add_f32_e32 v132, v132, v175
	v_add_f32_e32 v134, v134, v176
	v_add_f32_e32 v136, v136, v177
	v_add_f32_e32 v138, v138, v178
	v_add_f32_e32 v140, v140, v179
	v_add_f32_e32 v142, v142, v180
	v_add_f32_e32 v144, v144, v181
	v_fmamk_f32 v130, v130, 0x3a000000, v243
	v_fmamk_f32 v132, v132, 0x3a000000, v243
	v_fmamk_f32 v134, v134, 0x3a000000, v243
	v_fmamk_f32 v136, v136, 0x3a000000, v243
	v_fmamk_f32 v138, v138, 0x3a000000, v243
	v_fmamk_f32 v140, v140, 0x3a000000, v243
	v_fmamk_f32 v142, v142, 0x3a000000, v243
	v_fmamk_f32 v144, v144, 0x3a000000, v243
	v_rsq_f32_e32 v130, v130
	v_rsq_f32_e32 v132, v132
	v_rsq_f32_e32 v134, v134
	v_rsq_f32_e32 v136, v136
	v_rsq_f32_e32 v138, v138
	v_rsq_f32_e32 v140, v140
	v_rsq_f32_e32 v142, v142
	v_rsq_f32_e32 v144, v144
	s_nop 0
	v_pk_mul_f32 v[126:127], v[126:127], v[130:131] op_sel_hi:[1,0]
	v_pk_mul_f32 v[128:129], v[128:129], v[130:131] op_sel_hi:[1,0]
	v_pk_mul_f32 v[62:63], v[62:63], v[130:131] op_sel_hi:[1,0]
	v_pk_mul_f32 v[64:65], v[64:65], v[130:131] op_sel_hi:[1,0]
	v_pk_mul_f32 v[122:123], v[122:123], v[130:131] op_sel_hi:[1,0]
	v_pk_mul_f32 v[124:125], v[124:125], v[130:131] op_sel_hi:[1,0]
	v_pk_mul_f32 v[54:55], v[54:55], v[130:131] op_sel_hi:[1,0]
	v_pk_mul_f32 v[56:57], v[56:57], v[130:131] op_sel_hi:[1,0]
	v_pk_mul_f32 v[118:119], v[118:119], v[132:133] op_sel_hi:[1,0]
	v_pk_mul_f32 v[120:121], v[120:121], v[132:133] op_sel_hi:[1,0]
	v_pk_mul_f32 v[58:59], v[58:59], v[132:133] op_sel_hi:[1,0]
	v_pk_mul_f32 v[60:61], v[60:61], v[132:133] op_sel_hi:[1,0]
	v_pk_mul_f32 v[114:115], v[114:115], v[132:133] op_sel_hi:[1,0]
	v_pk_mul_f32 v[116:117], v[116:117], v[132:133] op_sel_hi:[1,0]
	v_pk_mul_f32 v[50:51], v[50:51], v[132:133] op_sel_hi:[1,0]
	v_pk_mul_f32 v[52:53], v[52:53], v[132:133] op_sel_hi:[1,0]
	v_pk_mul_f32 v[110:111], v[110:111], v[134:135] op_sel_hi:[1,0]
	v_pk_mul_f32 v[112:113], v[112:113], v[134:135] op_sel_hi:[1,0]
	v_pk_mul_f32 v[46:47], v[46:47], v[134:135] op_sel_hi:[1,0]
	v_pk_mul_f32 v[48:49], v[48:49], v[134:135] op_sel_hi:[1,0]
	v_pk_mul_f32 v[102:103], v[102:103], v[134:135] op_sel_hi:[1,0]
	v_pk_mul_f32 v[104:105], v[104:105], v[134:135] op_sel_hi:[1,0]
; __device__ __forceinline__ float sigmoid_f(float x) { return fast_rcp(1.0f + fast_exp2(-1.4426950409f * x)); }
;     __device__ __forceinline__ void operator()(f32x4 (&acc)[2][2][4][2], const Unit& u, int wr, int wc, int fr, int fq) const {
;     ...
;                 for (int bj = 0; bj < 2; ++bj) { acc[ai][bj][m][0] *= rstd; acc[ai][bj][m][1] *= rstd; } }
; #pragma unroll
;         for (int n = 0; n < 2; ++n) {
;             const int j4 = u.pn * 128 + wc * 32 + 8 * fq + 4 * n;
;             f32x4 kc[2][3], bc[2];
; #pragma unroll
;             for (int bj = 0; bj < 2; ++bj) { bc[bj] = *(const f32x4*)(cb + bj * FF + j4);
; #pragma unroll
;                 for (int w = 0; w < 3; ++w) kc[bj][w] = *(const f32x4*)(ck + w * NUP + bj * FF + j4); }
; #pragma unroll
;             for (int ai = 0; ai < 2; ++ai) {
;                 const int grp = u.pm * 4 + ai * 2 + wr;
; #pragma unroll
;                 for (int m = 0; m < 4; ++m) {
;                     f32x4 cv[2];
; #pragma unroll
;                     for (int bj = 0; bj < 2; ++bj) {
;                         const f32x4 cur = acc[ai][bj][m][n], lo = acc[ai][bj][m > 0 ? m - 1 : 0][n], hi = acc[ai][bj][m < 3 ? m + 1 : 3][n];
;                         f32x4 pv, nv;
; #pragma unroll
;                         for (int idx = 0; idx < 4; ++idx) {
;                             const float y = (fr == 15) ? lo[idx] : cur[idx], z = (fr == 0) ? hi[idx] : cur[idx];
;                             pv[idx] = __int_as_float(__builtin_amdgcn_update_dpp(0, __float_as_int(y), 0x121, 0xf, 0xf, false));
;                             nv[idx] = __int_as_float(__builtin_amdgcn_update_dpp(0, __float_as_int(z), 0x12f, 0xf, 0xf, false));
;                         }
;                         cv[bj] = kc[bj][0] * pv + kc[bj][1] * cur + kc[bj][2] * nv + bc[bj];
;                     }
;                     const int row = row0 + ai * HALF + m * 16;
;                     const bool edge = (m == 0 && fr == 0) || (m == 3 && fr == 15);
;                     if (!edge) { const f32x4 gt = cv[0], vl = cv[1];
;                         u32x2 w; w.x = cvt_pk_bf16(gt[0] * sigmoid_f(gt[0]) * vl[0], gt[1] * sigmoid_f(gt[1]) * vl[1]); w.y = cvt_pk_bf16(gt[2] * sigmoid_f(gt[2]) * vl[2], gt[3] * sigmoid_f(gt[3]) * vl[3]);
;                         *(u32x2*)(ACT + (size_t)row * FF + j4) = w; }
;                     if (m == 0 && fr < 2) {
; #pragma unroll
	v_pk_mul_f32 v[38:39], v[38:39], v[134:135] op_sel_hi:[1,0]
	v_pk_mul_f32 v[40:41], v[40:41], v[134:135] op_sel_hi:[1,0]
	v_pk_mul_f32 v[106:107], v[106:107], v[136:137] op_sel_hi:[1,0]
	v_pk_mul_f32 v[108:109], v[108:109], v[136:137] op_sel_hi:[1,0]
	v_pk_mul_f32 v[42:43], v[42:43], v[136:137] op_sel_hi:[1,0]
	v_pk_mul_f32 v[44:45], v[44:45], v[136:137] op_sel_hi:[1,0]
	v_pk_mul_f32 v[98:99], v[98:99], v[136:137] op_sel_hi:[1,0]
	v_pk_mul_f32 v[100:101], v[100:101], v[136:137] op_sel_hi:[1,0]
	v_pk_mul_f32 v[34:35], v[34:35], v[136:137] op_sel_hi:[1,0]
	v_pk_mul_f32 v[36:37], v[36:37], v[136:137] op_sel_hi:[1,0]
	v_pk_mul_f32 v[94:95], v[94:95], v[138:139] op_sel_hi:[1,0]
	v_pk_mul_f32 v[96:97], v[96:97], v[138:139] op_sel_hi:[1,0]
	v_pk_mul_f32 v[30:31], v[30:31], v[138:139] op_sel_hi:[1,0]
	v_pk_mul_f32 v[32:33], v[32:33], v[138:139] op_sel_hi:[1,0]
	v_pk_mul_f32 v[86:87], v[86:87], v[138:139] op_sel_hi:[1,0]
	v_pk_mul_f32 v[88:89], v[88:89], v[138:139] op_sel_hi:[1,0]
	v_pk_mul_f32 v[22:23], v[22:23], v[138:139] op_sel_hi:[1,0]
	v_pk_mul_f32 v[24:25], v[24:25], v[138:139] op_sel_hi:[1,0]
	v_pk_mul_f32 v[90:91], v[90:91], v[140:141] op_sel_hi:[1,0]
	v_pk_mul_f32 v[92:93], v[92:93], v[140:141] op_sel_hi:[1,0]
	v_pk_mul_f32 v[26:27], v[26:27], v[140:141] op_sel_hi:[1,0]
	v_pk_mul_f32 v[28:29], v[28:29], v[140:141] op_sel_hi:[1,0]
	v_pk_mul_f32 v[82:83], v[82:83], v[140:141] op_sel_hi:[1,0]
	v_pk_mul_f32 v[84:85], v[84:85], v[140:141] op_sel_hi:[1,0]
	v_pk_mul_f32 v[18:19], v[18:19], v[140:141] op_sel_hi:[1,0]
	v_pk_mul_f32 v[20:21], v[20:21], v[140:141] op_sel_hi:[1,0]
	v_pk_mul_f32 v[78:79], v[78:79], v[142:143] op_sel_hi:[1,0]
	v_pk_mul_f32 v[80:81], v[80:81], v[142:143] op_sel_hi:[1,0]
	v_pk_mul_f32 v[14:15], v[14:15], v[142:143] op_sel_hi:[1,0]
	v_pk_mul_f32 v[16:17], v[16:17], v[142:143] op_sel_hi:[1,0]
	v_pk_mul_f32 v[70:71], v[70:71], v[142:143] op_sel_hi:[1,0]
	v_pk_mul_f32 v[72:73], v[72:73], v[142:143] op_sel_hi:[1,0]
	v_pk_mul_f32 v[6:7], v[6:7], v[142:143] op_sel_hi:[1,0]
	v_pk_mul_f32 v[8:9], v[8:9], v[142:143] op_sel_hi:[1,0]
	v_pk_mul_f32 v[74:75], v[74:75], v[144:145] op_sel_hi:[1,0]
	v_pk_mul_f32 v[76:77], v[76:77], v[144:145] op_sel_hi:[1,0]
	v_pk_mul_f32 v[10:11], v[10:11], v[144:145] op_sel_hi:[1,0]
	v_pk_mul_f32 v[12:13], v[12:13], v[144:145] op_sel_hi:[1,0]
	v_pk_mul_f32 v[66:67], v[66:67], v[144:145] op_sel_hi:[1,0]
	v_pk_mul_f32 v[68:69], v[68:69], v[144:145] op_sel_hi:[1,0]
	v_pk_mul_f32 v[2:3], v[2:3], v[144:145] op_sel_hi:[1,0]
	v_pk_mul_f32 v[4:5], v[4:5], v[144:145] op_sel_hi:[1,0]
	s_mov_b32 s34, 0xbfb8aa3b
	s_mov_b32 s35, 0xbfb8aa3b
	s_mov_b32 s36, 1.0
	s_mov_b32 s37, 1.0
	v_lshl_add_u32 v238, s12, 8, v247
	v_mul_u32_u24_e32 v238, 0x2b00, v238
	v_add_u32_e32 v238, v238, v252
	s_lshl_b32 s13, s12, 4
	s_add_i32 s13, s13, s92
	v_add_u32_e32 v253, s13, v246
	v_mul_u32_u24_e32 v253, 0x5600, v253
	v_add_u32_e32 v253, v253, v252
	v_add_u32_e32 v239, 0x2b00, v253
	v_cvt_pk_bf16_f32 v230, v126, v127
	v_cvt_pk_bf16_f32 v231, v128, v129
	v_cvt_pk_bf16_f32 v232, v62, v63
	v_cvt_pk_bf16_f32 v233, v64, v65
	s_and_saveexec_b64 s[16:17], s[46:47]
	global_store_dwordx4 v253, v[230:233], s[54:55]
	s_or_b64 exec, exec, s[16:17]
	v_cvt_pk_bf16_f32 v234, v122, v123
	v_cvt_pk_bf16_f32 v235, v124, v125
	v_cvt_pk_bf16_f32 v236, v54, v55
	v_cvt_pk_bf16_f32 v237, v56, v57
	s_and_saveexec_b64 s[16:17], s[46:47]
	global_store_dwordx4 v239, v[234:237], s[54:55]
	s_or_b64 exec, exec, s[16:17]
	v_add_u32_e32 v253, s13, v246
	v_add_u32_e32 v253, 8, v253
	v_mul_u32_u24_e32 v253, 0x5600, v253
	v_add_u32_e32 v253, v253, v252
	v_add_u32_e32 v239, 0x2b00, v253
	v_cvt_pk_bf16_f32 v214, v94, v95
	v_cvt_pk_bf16_f32 v215, v96, v97
	v_cvt_pk_bf16_f32 v216, v30, v31
	v_cvt_pk_bf16_f32 v217, v32, v33
	s_and_saveexec_b64 s[16:17], s[46:47]
	global_store_dwordx4 v253, v[214:217], s[54:55]
	s_or_b64 exec, exec, s[16:17]
	v_cvt_pk_bf16_f32 v218, v86, v87
	v_cvt_pk_bf16_f32 v219, v88, v89
	v_cvt_pk_bf16_f32 v220, v22, v23
	v_cvt_pk_bf16_f32 v221, v24, v25
	s_and_saveexec_b64 s[16:17], s[46:47]
	global_store_dwordx4 v239, v[218:221], s[54:55]
	s_or_b64 exec, exec, s[16:17]
	v_add_u32_e32 v253, s13, v249
	v_mul_u32_u24_e32 v253, 0x5600, v253
	v_add_u32_e32 v253, v253, v252
	v_add_u32_e32 v239, 0x2b00, v253
	v_cvt_pk_bf16_f32 v230, v106, v107
	v_cvt_pk_bf16_f32 v231, v108, v109
	v_cvt_pk_bf16_f32 v232, v42, v43
	v_cvt_pk_bf16_f32 v233, v44, v45
	s_and_saveexec_b64 s[16:17], s[48:49]
	global_store_dwordx4 v253, v[230:233], s[54:55]
	s_or_b64 exec, exec, s[16:17]
	v_cvt_pk_bf16_f32 v234, v98, v99
	v_cvt_pk_bf16_f32 v235, v100, v101
	v_cvt_pk_bf16_f32 v236, v34, v35
	v_cvt_pk_bf16_f32 v237, v36, v37
	s_and_saveexec_b64 s[16:17], s[48:49]
	global_store_dwordx4 v239, v[234:237], s[54:55]
	s_or_b64 exec, exec, s[16:17]
	v_add_u32_e32 v253, s13, v249
	v_add_u32_e32 v253, 8, v253
	v_mul_u32_u24_e32 v253, 0x5600, v253
	v_add_u32_e32 v253, v253, v252
	v_add_u32_e32 v239, 0x2b00, v253
	v_cvt_pk_bf16_f32 v214, v74, v75
	v_cvt_pk_bf16_f32 v215, v76, v77
	v_cvt_pk_bf16_f32 v216, v10, v11
	v_cvt_pk_bf16_f32 v217, v12, v13
	s_and_saveexec_b64 s[16:17], s[48:49]
	global_store_dwordx4 v253, v[214:217], s[54:55]
	s_or_b64 exec, exec, s[16:17]
	v_cvt_pk_bf16_f32 v218, v66, v67
	v_cvt_pk_bf16_f32 v219, v68, v69
	v_cvt_pk_bf16_f32 v220, v2, v3
	v_cvt_pk_bf16_f32 v221, v4, v5
	s_and_saveexec_b64 s[16:17], s[48:49]
	global_store_dwordx4 v239, v[218:221], s[54:55]
	s_or_b64 exec, exec, s[16:17]
	s_waitcnt vmcnt(8)
; __device__ __forceinline__ unsigned cvt_pk_bf16(float lo, float hi) { unsigned r; asm volatile("v_cvt_pk_bf16_f32 %0, %1, %2" : "=v"(r) : "v"(lo), "v"(hi)); return r; }
; __device__ __forceinline__ float sigmoid_f(float x) { return fast_rcp(1.0f + fast_exp2(-1.4426950409f * x)); }
;     __device__ __forceinline__ void operator()(f32x4 (&acc)[2][2][4][2], const Unit& u, int wr, int wc, int fr, int fq) const {
;     ...
;                 for (int m = 0; m < 4; ++m) {
;                     f32x4 cv[2];
; #pragma unroll
;                     for (int bj = 0; bj < 2; ++bj) {
;                         const f32x4 cur = acc[ai][bj][m][n], lo = acc[ai][bj][m > 0 ? m - 1 : 0][n], hi = acc[ai][bj][m < 3 ? m + 1 : 3][n];
;                         f32x4 pv, nv;
; #pragma unroll
;                         for (int idx = 0; idx < 4; ++idx) {
;                             const float y = (fr == 15) ? lo[idx] : cur[idx], z = (fr == 0) ? hi[idx] : cur[idx];
;                             pv[idx] = __int_as_float(__builtin_amdgcn_update_dpp(0, __float_as_int(y), 0x121, 0xf, 0xf, false));
;                             nv[idx] = __int_as_float(__builtin_amdgcn_update_dpp(0, __float_as_int(z), 0x12f, 0xf, 0xf, false));
;                         }
;                         cv[bj] = kc[bj][0] * pv + kc[bj][1] * cur + kc[bj][2] * nv + bc[bj];
;                     }
;                     const int row = row0 + ai * HALF + m * 16;
;                     const bool edge = (m == 0 && fr == 0) || (m == 3 && fr == 15);
;                     if (!edge) { const f32x4 gt = cv[0], vl = cv[1];
;                         u32x2 w; w.x = cvt_pk_bf16(gt[0] * sigmoid_f(gt[0]) * vl[0], gt[1] * sigmoid_f(gt[1]) * vl[1]); w.y = cvt_pk_bf16(gt[2] * sigmoid_f(gt[2]) * vl[2], gt[3] * sigmoid_f(gt[3]) * vl[3]);
;                         *(u32x2*)(ACT + (size_t)row * FF + j4) = w; }
	v_cndmask_b32_e64 v214, 0, v182, s[42:43]
	v_cndmask_b32_e64 v215, 0, v183, s[42:43]
	v_cndmask_b32_e64 v216, 0, v184, s[42:43]
	v_cndmask_b32_e64 v217, 0, v185, s[42:43]
	v_cndmask_b32_e64 v218, 0, v198, s[42:43]
	v_cndmask_b32_e64 v219, 0, v199, s[42:43]
	v_cndmask_b32_e64 v220, 0, v200, s[42:43]
	v_cndmask_b32_e64 v221, 0, v201, s[42:43]
	v_cndmask_b32_e64 v222, 0, v190, s[38:39]
	v_cndmask_b32_e64 v223, 0, v191, s[38:39]
	v_cndmask_b32_e64 v224, 0, v192, s[38:39]
	v_cndmask_b32_e64 v225, 0, v193, s[38:39]
	v_cndmask_b32_e64 v226, 0, v206, s[38:39]
	v_cndmask_b32_e64 v227, 0, v207, s[38:39]
	v_cndmask_b32_e64 v228, 0, v208, s[38:39]
	v_cndmask_b32_e64 v229, 0, v209, s[38:39]
	v_pk_fma_f32 v[230:231], v[126:127], v[186:187], v[194:195]
	v_pk_fma_f32 v[232:233], v[128:129], v[188:189], v[196:197]
	v_pk_fma_f32 v[234:235], v[122:123], v[202:203], v[210:211]
	v_pk_fma_f32 v[236:237], v[124:125], v[204:205], v[212:213]
	v_fmac_f32_dpp v230, v126, v182 row_shr:1 row_mask:0xf bank_mask:0xf
	v_fmac_f32_dpp v231, v127, v183 row_shr:1 row_mask:0xf bank_mask:0xf
	v_fmac_f32_dpp v232, v128, v184 row_shr:1 row_mask:0xf bank_mask:0xf
	v_fmac_f32_dpp v233, v129, v185 row_shr:1 row_mask:0xf bank_mask:0xf
	v_fmac_f32_dpp v234, v122, v198 row_shr:1 row_mask:0xf bank_mask:0xf
	v_fmac_f32_dpp v235, v123, v199 row_shr:1 row_mask:0xf bank_mask:0xf
	v_fmac_f32_dpp v236, v124, v200 row_shr:1 row_mask:0xf bank_mask:0xf
	v_fmac_f32_dpp v237, v125, v201 row_shr:1 row_mask:0xf bank_mask:0xf
	v_fmac_f32_dpp v230, v126, v190 row_shl:1 row_mask:0xf bank_mask:0xf
	v_fmac_f32_dpp v231, v127, v191 row_shl:1 row_mask:0xf bank_mask:0xf
	v_fmac_f32_dpp v232, v128, v192 row_shl:1 row_mask:0xf bank_mask:0xf
	v_fmac_f32_dpp v233, v129, v193 row_shl:1 row_mask:0xf bank_mask:0xf
	v_fmac_f32_dpp v234, v122, v206 row_shl:1 row_mask:0xf bank_mask:0xf
	v_fmac_f32_dpp v235, v123, v207 row_shl:1 row_mask:0xf bank_mask:0xf
	v_fmac_f32_dpp v236, v124, v208 row_shl:1 row_mask:0xf bank_mask:0xf
	v_fmac_f32_dpp v237, v125, v209 row_shl:1 row_mask:0xf bank_mask:0xf
	v_fmac_f32_dpp v230, v118, v222 row_ror:15 row_mask:0xf bank_mask:0xf
	v_fmac_f32_dpp v231, v119, v223 row_ror:15 row_mask:0xf bank_mask:0xf
	v_fmac_f32_dpp v232, v120, v224 row_ror:15 row_mask:0xf bank_mask:0xf
	v_fmac_f32_dpp v233, v121, v225 row_ror:15 row_mask:0xf bank_mask:0xf
	v_fmac_f32_dpp v234, v114, v226 row_ror:15 row_mask:0xf bank_mask:0xf
	v_fmac_f32_dpp v235, v115, v227 row_ror:15 row_mask:0xf bank_mask:0xf
	v_fmac_f32_dpp v236, v116, v228 row_ror:15 row_mask:0xf bank_mask:0xf
	v_fmac_f32_dpp v237, v117, v229 row_ror:15 row_mask:0xf bank_mask:0xf
	v_pk_mul_f32 v[174:175], v[230:231], s[34:35]
	v_pk_mul_f32 v[176:177], v[232:233], s[34:35]
	v_exp_f32_e32 v174, v174
	v_exp_f32_e32 v175, v175
	v_exp_f32_e32 v176, v176
	v_exp_f32_e32 v177, v177
	v_pk_add_f32 v[174:175], v[174:175], s[36:37]
	v_pk_add_f32 v[176:177], v[176:177], s[36:37]
	v_rcp_f32_e32 v174, v174
	v_rcp_f32_e32 v175, v175
	v_rcp_f32_e32 v176, v176
	v_rcp_f32_e32 v177, v177
	v_pk_mul_f32 v[174:175], v[230:231], v[174:175]
	v_pk_mul_f32 v[176:177], v[232:233], v[176:177]
	v_pk_mul_f32 v[174:175], v[174:175], v[234:235]
	v_pk_mul_f32 v[176:177], v[176:177], v[236:237]
	v_cvt_pk_bf16_f32 v178, v174, v175
	v_cvt_pk_bf16_f32 v179, v176, v177
	s_and_saveexec_b64 s[16:17], s[44:45]
	global_store_dwordx2 v238, v[178:179], s[30:31]
	s_or_b64 exec, exec, s[16:17]
	v_pk_fma_f32 v[230:231], v[118:119], v[186:187], v[194:195]
	v_pk_fma_f32 v[232:233], v[120:121], v[188:189], v[196:197]
	v_pk_fma_f32 v[234:235], v[114:115], v[202:203], v[210:211]
	v_pk_fma_f32 v[236:237], v[116:117], v[204:205], v[212:213]
	v_fmac_f32_dpp v230, v118, v182 row_shr:1 row_mask:0xf bank_mask:0xf
	v_fmac_f32_dpp v231, v119, v183 row_shr:1 row_mask:0xf bank_mask:0xf
	v_fmac_f32_dpp v232, v120, v184 row_shr:1 row_mask:0xf bank_mask:0xf
	v_fmac_f32_dpp v233, v121, v185 row_shr:1 row_mask:0xf bank_mask:0xf
	v_fmac_f32_dpp v234, v114, v198 row_shr:1 row_mask:0xf bank_mask:0xf
	v_fmac_f32_dpp v235, v115, v199 row_shr:1 row_mask:0xf bank_mask:0xf
	v_fmac_f32_dpp v236, v116, v200 row_shr:1 row_mask:0xf bank_mask:0xf
	v_fmac_f32_dpp v237, v117, v201 row_shr:1 row_mask:0xf bank_mask:0xf
	v_fmac_f32_dpp v230, v118, v190 row_shl:1 row_mask:0xf bank_mask:0xf
	v_fmac_f32_dpp v231, v119, v191 row_shl:1 row_mask:0xf bank_mask:0xf
	v_fmac_f32_dpp v232, v120, v192 row_shl:1 row_mask:0xf bank_mask:0xf
	v_fmac_f32_dpp v233, v121, v193 row_shl:1 row_mask:0xf bank_mask:0xf
	v_fmac_f32_dpp v234, v114, v206 row_shl:1 row_mask:0xf bank_mask:0xf
	v_fmac_f32_dpp v235, v115, v207 row_shl:1 row_mask:0xf bank_mask:0xf
	v_fmac_f32_dpp v236, v116, v208 row_shl:1 row_mask:0xf bank_mask:0xf
	v_fmac_f32_dpp v237, v117, v209 row_shl:1 row_mask:0xf bank_mask:0xf
	v_fmac_f32_dpp v230, v126, v214 row_ror:1 row_mask:0xf bank_mask:0xf
	v_fmac_f32_dpp v231, v127, v215 row_ror:1 row_mask:0xf bank_mask:0xf
	v_fmac_f32_dpp v232, v128, v216 row_ror:1 row_mask:0xf bank_mask:0xf
	v_fmac_f32_dpp v233, v129, v217 row_ror:1 row_mask:0xf bank_mask:0xf
	v_fmac_f32_dpp v234, v122, v218 row_ror:1 row_mask:0xf bank_mask:0xf
	v_fmac_f32_dpp v235, v123, v219 row_ror:1 row_mask:0xf bank_mask:0xf
	v_fmac_f32_dpp v236, v124, v220 row_ror:1 row_mask:0xf bank_mask:0xf
	v_fmac_f32_dpp v237, v125, v221 row_ror:1 row_mask:0xf bank_mask:0xf
	v_fmac_f32_dpp v230, v110, v222 row_ror:15 row_mask:0xf bank_mask:0xf
	v_fmac_f32_dpp v231, v111, v223 row_ror:15 row_mask:0xf bank_mask:0xf
	v_fmac_f32_dpp v232, v112, v224 row_ror:15 row_mask:0xf bank_mask:0xf
	v_fmac_f32_dpp v233, v113, v225 row_ror:15 row_mask:0xf bank_mask:0xf
; __device__ __forceinline__ unsigned cvt_pk_bf16(float lo, float hi) { unsigned r; asm volatile("v_cvt_pk_bf16_f32 %0, %1, %2" : "=v"(r) : "v"(lo), "v"(hi)); return r; }
; __device__ __forceinline__ float sigmoid_f(float x) { return fast_rcp(1.0f + fast_exp2(-1.4426950409f * x)); }
;     __device__ __forceinline__ void operator()(f32x4 (&acc)[2][2][4][2], const Unit& u, int wr, int wc, int fr, int fq) const {
;     ...
;                 for (int m = 0; m < 4; ++m) {
;                     f32x4 cv[2];
; #pragma unroll
;                     for (int bj = 0; bj < 2; ++bj) {
;                         const f32x4 cur = acc[ai][bj][m][n], lo = acc[ai][bj][m > 0 ? m - 1 : 0][n], hi = acc[ai][bj][m < 3 ? m + 1 : 3][n];
;                         f32x4 pv, nv;
; #pragma unroll
;                         for (int idx = 0; idx < 4; ++idx) {
;                             const float y = (fr == 15) ? lo[idx] : cur[idx], z = (fr == 0) ? hi[idx] : cur[idx];
;                             pv[idx] = __int_as_float(__builtin_amdgcn_update_dpp(0, __float_as_int(y), 0x121, 0xf, 0xf, false));
;                             nv[idx] = __int_as_float(__builtin_amdgcn_update_dpp(0, __float_as_int(z), 0x12f, 0xf, 0xf, false));
;                         }
;                         cv[bj] = kc[bj][0] * pv + kc[bj][1] * cur + kc[bj][2] * nv + bc[bj];
;                     }
;                     const int row = row0 + ai * HALF + m * 16;
;                     const bool edge = (m == 0 && fr == 0) || (m == 3 && fr == 15);
;                     if (!edge) { const f32x4 gt = cv[0], vl = cv[1];
;                         u32x2 w; w.x = cvt_pk_bf16(gt[0] * sigmoid_f(gt[0]) * vl[0], gt[1] * sigmoid_f(gt[1]) * vl[1]); w.y = cvt_pk_bf16(gt[2] * sigmoid_f(gt[2]) * vl[2], gt[3] * sigmoid_f(gt[3]) * vl[3]);
;                         *(u32x2*)(ACT + (size_t)row * FF + j4) = w; }
	v_fmac_f32_dpp v234, v102, v226 row_ror:15 row_mask:0xf bank_mask:0xf
	v_fmac_f32_dpp v235, v103, v227 row_ror:15 row_mask:0xf bank_mask:0xf
	v_fmac_f32_dpp v236, v104, v228 row_ror:15 row_mask:0xf bank_mask:0xf
	v_fmac_f32_dpp v237, v105, v229 row_ror:15 row_mask:0xf bank_mask:0xf
	v_pk_mul_f32 v[174:175], v[230:231], s[34:35]
	v_pk_mul_f32 v[176:177], v[232:233], s[34:35]
	v_exp_f32_e32 v174, v174
	v_exp_f32_e32 v175, v175
	v_exp_f32_e32 v176, v176
	v_exp_f32_e32 v177, v177
	v_pk_add_f32 v[174:175], v[174:175], s[36:37]
	v_pk_add_f32 v[176:177], v[176:177], s[36:37]
	v_rcp_f32_e32 v174, v174
	v_rcp_f32_e32 v175, v175
	v_rcp_f32_e32 v176, v176
	v_rcp_f32_e32 v177, v177
	v_pk_mul_f32 v[174:175], v[230:231], v[174:175]
	v_pk_mul_f32 v[176:177], v[232:233], v[176:177]
	v_pk_mul_f32 v[174:175], v[174:175], v[234:235]
	v_pk_mul_f32 v[176:177], v[176:177], v[236:237]
	v_cvt_pk_bf16_f32 v180, v174, v175
	v_cvt_pk_bf16_f32 v181, v176, v177
	v_add_u32_e32 v239, 0x2b000, v238
	global_store_dwordx2 v239, v[180:181], s[30:31]
	v_pk_fma_f32 v[230:231], v[110:111], v[186:187], v[194:195]
	v_pk_fma_f32 v[232:233], v[112:113], v[188:189], v[196:197]
	v_pk_fma_f32 v[234:235], v[102:103], v[202:203], v[210:211]
	v_pk_fma_f32 v[236:237], v[104:105], v[204:205], v[212:213]
	v_fmac_f32_dpp v230, v110, v182 row_shr:1 row_mask:0xf bank_mask:0xf
	v_fmac_f32_dpp v231, v111, v183 row_shr:1 row_mask:0xf bank_mask:0xf
	v_fmac_f32_dpp v232, v112, v184 row_shr:1 row_mask:0xf bank_mask:0xf
	v_fmac_f32_dpp v233, v113, v185 row_shr:1 row_mask:0xf bank_mask:0xf
	v_fmac_f32_dpp v234, v102, v198 row_shr:1 row_mask:0xf bank_mask:0xf
	v_fmac_f32_dpp v235, v103, v199 row_shr:1 row_mask:0xf bank_mask:0xf
	v_fmac_f32_dpp v236, v104, v200 row_shr:1 row_mask:0xf bank_mask:0xf
	v_fmac_f32_dpp v237, v105, v201 row_shr:1 row_mask:0xf bank_mask:0xf
	v_fmac_f32_dpp v230, v110, v190 row_shl:1 row_mask:0xf bank_mask:0xf
	v_fmac_f32_dpp v231, v111, v191 row_shl:1 row_mask:0xf bank_mask:0xf
	v_fmac_f32_dpp v232, v112, v192 row_shl:1 row_mask:0xf bank_mask:0xf
	v_fmac_f32_dpp v233, v113, v193 row_shl:1 row_mask:0xf bank_mask:0xf
	v_fmac_f32_dpp v234, v102, v206 row_shl:1 row_mask:0xf bank_mask:0xf
	v_fmac_f32_dpp v235, v103, v207 row_shl:1 row_mask:0xf bank_mask:0xf
	v_fmac_f32_dpp v236, v104, v208 row_shl:1 row_mask:0xf bank_mask:0xf
	v_fmac_f32_dpp v237, v105, v209 row_shl:1 row_mask:0xf bank_mask:0xf
	v_fmac_f32_dpp v230, v118, v214 row_ror:1 row_mask:0xf bank_mask:0xf
	v_fmac_f32_dpp v231, v119, v215 row_ror:1 row_mask:0xf bank_mask:0xf
	v_fmac_f32_dpp v232, v120, v216 row_ror:1 row_mask:0xf bank_mask:0xf
	v_fmac_f32_dpp v233, v121, v217 row_ror:1 row_mask:0xf bank_mask:0xf
	v_fmac_f32_dpp v234, v114, v218 row_ror:1 row_mask:0xf bank_mask:0xf
	v_fmac_f32_dpp v235, v115, v219 row_ror:1 row_mask:0xf bank_mask:0xf
	v_fmac_f32_dpp v236, v116, v220 row_ror:1 row_mask:0xf bank_mask:0xf
	v_fmac_f32_dpp v237, v117, v221 row_ror:1 row_mask:0xf bank_mask:0xf
	v_fmac_f32_dpp v230, v106, v222 row_ror:15 row_mask:0xf bank_mask:0xf
	v_fmac_f32_dpp v231, v107, v223 row_ror:15 row_mask:0xf bank_mask:0xf
	v_fmac_f32_dpp v232, v108, v224 row_ror:15 row_mask:0xf bank_mask:0xf
	v_fmac_f32_dpp v233, v109, v225 row_ror:15 row_mask:0xf bank_mask:0xf
	v_fmac_f32_dpp v234, v98, v226 row_ror:15 row_mask:0xf bank_mask:0xf
	v_fmac_f32_dpp v235, v99, v227 row_ror:15 row_mask:0xf bank_mask:0xf
	v_fmac_f32_dpp v236, v100, v228 row_ror:15 row_mask:0xf bank_mask:0xf
	v_fmac_f32_dpp v237, v101, v229 row_ror:15 row_mask:0xf bank_mask:0xf
	v_pk_mul_f32 v[174:175], v[230:231], s[34:35]
	v_pk_mul_f32 v[176:177], v[232:233], s[34:35]
	v_exp_f32_e32 v174, v174
	v_exp_f32_e32 v175, v175
	v_exp_f32_e32 v176, v176
	v_exp_f32_e32 v177, v177
	v_pk_add_f32 v[174:175], v[174:175], s[36:37]
	v_pk_add_f32 v[176:177], v[176:177], s[36:37]
	v_rcp_f32_e32 v174, v174
	v_rcp_f32_e32 v175, v175
	v_rcp_f32_e32 v176, v176
	v_rcp_f32_e32 v177, v177
	v_pk_mul_f32 v[174:175], v[230:231], v[174:175]
	v_pk_mul_f32 v[176:177], v[232:233], v[176:177]
	v_pk_mul_f32 v[174:175], v[174:175], v[234:235]
	v_pk_mul_f32 v[176:177], v[176:177], v[236:237]
	v_cvt_pk_bf16_f32 v178, v174, v175
	v_cvt_pk_bf16_f32 v179, v176, v177
	v_add_u32_e32 v239, 0x56000, v238
	global_store_dwordx2 v239, v[178:179], s[30:31]
	v_pk_fma_f32 v[230:231], v[106:107], v[186:187], v[194:195]
	v_pk_fma_f32 v[232:233], v[108:109], v[188:189], v[196:197]
	v_pk_fma_f32 v[234:235], v[98:99], v[202:203], v[210:211]
	v_pk_fma_f32 v[236:237], v[100:101], v[204:205], v[212:213]
	v_fmac_f32_dpp v230, v106, v182 row_shr:1 row_mask:0xf bank_mask:0xf
	v_fmac_f32_dpp v231, v107, v183 row_shr:1 row_mask:0xf bank_mask:0xf
	v_fmac_f32_dpp v232, v108, v184 row_shr:1 row_mask:0xf bank_mask:0xf
	v_fmac_f32_dpp v233, v109, v185 row_shr:1 row_mask:0xf bank_mask:0xf
	v_fmac_f32_dpp v234, v98, v198 row_shr:1 row_mask:0xf bank_mask:0xf
	v_fmac_f32_dpp v235, v99, v199 row_shr:1 row_mask:0xf bank_mask:0xf
	v_fmac_f32_dpp v236, v100, v200 row_shr:1 row_mask:0xf bank_mask:0xf
	v_fmac_f32_dpp v237, v101, v201 row_shr:1 row_mask:0xf bank_mask:0xf
	v_fmac_f32_dpp v230, v106, v190 row_shl:1 row_mask:0xf bank_mask:0xf
	v_fmac_f32_dpp v231, v107, v191 row_shl:1 row_mask:0xf bank_mask:0xf
	v_fmac_f32_dpp v232, v108, v192 row_shl:1 row_mask:0xf bank_mask:0xf
	v_fmac_f32_dpp v233, v109, v193 row_shl:1 row_mask:0xf bank_mask:0xf
	v_fmac_f32_dpp v234, v98, v206 row_shl:1 row_mask:0xf bank_mask:0xf
	v_fmac_f32_dpp v235, v99, v207 row_shl:1 row_mask:0xf bank_mask:0xf
	v_fmac_f32_dpp v236, v100, v208 row_shl:1 row_mask:0xf bank_mask:0xf
	v_fmac_f32_dpp v237, v101, v209 row_shl:1 row_mask:0xf bank_mask:0xf
; __device__ __forceinline__ unsigned cvt_pk_bf16(float lo, float hi) { unsigned r; asm volatile("v_cvt_pk_bf16_f32 %0, %1, %2" : "=v"(r) : "v"(lo), "v"(hi)); return r; }
; __device__ __forceinline__ float sigmoid_f(float x) { return fast_rcp(1.0f + fast_exp2(-1.4426950409f * x)); }
;     __device__ __forceinline__ void operator()(f32x4 (&acc)[2][2][4][2], const Unit& u, int wr, int wc, int fr, int fq) const {
;     ...
;             for (int bj = 0; bj < 2; ++bj) { bc[bj] = *(const f32x4*)(cb + bj * FF + j4);
; #pragma unroll
;                 for (int w = 0; w < 3; ++w) kc[bj][w] = *(const f32x4*)(ck + w * NUP + bj * FF + j4); }
;     ...
;                 for (int m = 0; m < 4; ++m) {
;                     f32x4 cv[2];
; #pragma unroll
;                     for (int bj = 0; bj < 2; ++bj) {
;                         const f32x4 cur = acc[ai][bj][m][n], lo = acc[ai][bj][m > 0 ? m - 1 : 0][n], hi = acc[ai][bj][m < 3 ? m + 1 : 3][n];
;                         f32x4 pv, nv;
; #pragma unroll
;                         for (int idx = 0; idx < 4; ++idx) {
;                             const float y = (fr == 15) ? lo[idx] : cur[idx], z = (fr == 0) ? hi[idx] : cur[idx];
;                             pv[idx] = __int_as_float(__builtin_amdgcn_update_dpp(0, __float_as_int(y), 0x121, 0xf, 0xf, false));
;                             nv[idx] = __int_as_float(__builtin_amdgcn_update_dpp(0, __float_as_int(z), 0x12f, 0xf, 0xf, false));
;                         }
;                         cv[bj] = kc[bj][0] * pv + kc[bj][1] * cur + kc[bj][2] * nv + bc[bj];
;                     }
;                     const int row = row0 + ai * HALF + m * 16;
;                     const bool edge = (m == 0 && fr == 0) || (m == 3 && fr == 15);
;                     if (!edge) { const f32x4 gt = cv[0], vl = cv[1];
;                         u32x2 w; w.x = cvt_pk_bf16(gt[0] * sigmoid_f(gt[0]) * vl[0], gt[1] * sigmoid_f(gt[1]) * vl[1]); w.y = cvt_pk_bf16(gt[2] * sigmoid_f(gt[2]) * vl[2], gt[3] * sigmoid_f(gt[3]) * vl[3]);
;                         *(u32x2*)(ACT + (size_t)row * FF + j4) = w; }
	v_fmac_f32_dpp v230, v110, v214 row_ror:1 row_mask:0xf bank_mask:0xf
	v_fmac_f32_dpp v231, v111, v215 row_ror:1 row_mask:0xf bank_mask:0xf
	v_fmac_f32_dpp v232, v112, v216 row_ror:1 row_mask:0xf bank_mask:0xf
	v_fmac_f32_dpp v233, v113, v217 row_ror:1 row_mask:0xf bank_mask:0xf
	v_fmac_f32_dpp v234, v102, v218 row_ror:1 row_mask:0xf bank_mask:0xf
	v_fmac_f32_dpp v235, v103, v219 row_ror:1 row_mask:0xf bank_mask:0xf
	v_fmac_f32_dpp v236, v104, v220 row_ror:1 row_mask:0xf bank_mask:0xf
	v_fmac_f32_dpp v237, v105, v221 row_ror:1 row_mask:0xf bank_mask:0xf
	v_pk_mul_f32 v[174:175], v[230:231], s[34:35]
	v_pk_mul_f32 v[176:177], v[232:233], s[34:35]
	v_exp_f32_e32 v174, v174
	v_exp_f32_e32 v175, v175
	v_exp_f32_e32 v176, v176
	v_exp_f32_e32 v177, v177
	v_pk_add_f32 v[174:175], v[174:175], s[36:37]
	v_pk_add_f32 v[176:177], v[176:177], s[36:37]
	v_rcp_f32_e32 v174, v174
	v_rcp_f32_e32 v175, v175
	v_rcp_f32_e32 v176, v176
	v_rcp_f32_e32 v177, v177
	v_pk_mul_f32 v[174:175], v[230:231], v[174:175]
	v_pk_mul_f32 v[176:177], v[232:233], v[176:177]
	v_pk_mul_f32 v[174:175], v[174:175], v[234:235]
	v_pk_mul_f32 v[176:177], v[176:177], v[236:237]
	v_cvt_pk_bf16_f32 v180, v174, v175
	v_cvt_pk_bf16_f32 v181, v176, v177
	v_add_u32_e32 v239, 0x81000, v238
	s_and_saveexec_b64 s[16:17], s[40:41]
	global_store_dwordx2 v239, v[180:181], s[30:31]
	s_or_b64 exec, exec, s[16:17]
	global_load_dwordx4 v[126:129], v242, s[18:19] offset:16
	global_load_dwordx4 v[118:121], v133, s[18:19] offset:16
	global_load_dwordx4 v[110:113], v137, s[18:19] offset:16
	global_load_dwordx4 v[106:109], v242, s[20:21] offset:16
	global_load_dwordx4 v[122:125], v131, s[18:19] offset:16
	global_load_dwordx4 v[114:117], v135, s[18:19] offset:16
	global_load_dwordx4 v[102:105], v139, s[18:19] offset:16
	global_load_dwordx4 v[98:101], v131, s[20:21] offset:16
	v_pk_fma_f32 v[230:231], v[94:95], v[186:187], v[194:195]
	v_pk_fma_f32 v[232:233], v[96:97], v[188:189], v[196:197]
	v_pk_fma_f32 v[234:235], v[86:87], v[202:203], v[210:211]
	v_pk_fma_f32 v[236:237], v[88:89], v[204:205], v[212:213]
	v_fmac_f32_dpp v230, v94, v182 row_shr:1 row_mask:0xf bank_mask:0xf
	v_fmac_f32_dpp v231, v95, v183 row_shr:1 row_mask:0xf bank_mask:0xf
	v_fmac_f32_dpp v232, v96, v184 row_shr:1 row_mask:0xf bank_mask:0xf
	v_fmac_f32_dpp v233, v97, v185 row_shr:1 row_mask:0xf bank_mask:0xf
	v_fmac_f32_dpp v234, v86, v198 row_shr:1 row_mask:0xf bank_mask:0xf
	v_fmac_f32_dpp v235, v87, v199 row_shr:1 row_mask:0xf bank_mask:0xf
	v_fmac_f32_dpp v236, v88, v200 row_shr:1 row_mask:0xf bank_mask:0xf
	v_fmac_f32_dpp v237, v89, v201 row_shr:1 row_mask:0xf bank_mask:0xf
	v_fmac_f32_dpp v230, v94, v190 row_shl:1 row_mask:0xf bank_mask:0xf
	v_fmac_f32_dpp v231, v95, v191 row_shl:1 row_mask:0xf bank_mask:0xf
	v_fmac_f32_dpp v232, v96, v192 row_shl:1 row_mask:0xf bank_mask:0xf
	v_fmac_f32_dpp v233, v97, v193 row_shl:1 row_mask:0xf bank_mask:0xf
	v_fmac_f32_dpp v234, v86, v206 row_shl:1 row_mask:0xf bank_mask:0xf
	v_fmac_f32_dpp v235, v87, v207 row_shl:1 row_mask:0xf bank_mask:0xf
	v_fmac_f32_dpp v236, v88, v208 row_shl:1 row_mask:0xf bank_mask:0xf
	v_fmac_f32_dpp v237, v89, v209 row_shl:1 row_mask:0xf bank_mask:0xf
	v_fmac_f32_dpp v230, v90, v222 row_ror:15 row_mask:0xf bank_mask:0xf
	v_fmac_f32_dpp v231, v91, v223 row_ror:15 row_mask:0xf bank_mask:0xf
	v_fmac_f32_dpp v232, v92, v224 row_ror:15 row_mask:0xf bank_mask:0xf
	v_fmac_f32_dpp v233, v93, v225 row_ror:15 row_mask:0xf bank_mask:0xf
	v_fmac_f32_dpp v234, v82, v226 row_ror:15 row_mask:0xf bank_mask:0xf
	v_fmac_f32_dpp v235, v83, v227 row_ror:15 row_mask:0xf bank_mask:0xf
	v_fmac_f32_dpp v236, v84, v228 row_ror:15 row_mask:0xf bank_mask:0xf
	v_fmac_f32_dpp v237, v85, v229 row_ror:15 row_mask:0xf bank_mask:0xf
	v_pk_mul_f32 v[174:175], v[230:231], s[34:35]
	v_pk_mul_f32 v[176:177], v[232:233], s[34:35]
	v_exp_f32_e32 v174, v174
	v_exp_f32_e32 v175, v175
	v_exp_f32_e32 v176, v176
	v_exp_f32_e32 v177, v177
	v_pk_add_f32 v[174:175], v[174:175], s[36:37]
	v_pk_add_f32 v[176:177], v[176:177], s[36:37]
	v_rcp_f32_e32 v174, v174
	v_rcp_f32_e32 v175, v175
	v_rcp_f32_e32 v176, v176
	v_rcp_f32_e32 v177, v177
	v_pk_mul_f32 v[174:175], v[230:231], v[174:175]
	v_pk_mul_f32 v[176:177], v[232:233], v[176:177]
	v_pk_mul_f32 v[174:175], v[174:175], v[234:235]
	v_pk_mul_f32 v[176:177], v[176:177], v[236:237]
	v_cvt_pk_bf16_f32 v180, v174, v175
	v_cvt_pk_bf16_f32 v181, v176, v177
	v_add_u32_e32 v239, 0x158000, v238
	s_and_saveexec_b64 s[16:17], s[44:45]
	global_store_dwordx2 v239, v[180:181], s[30:31]
	s_or_b64 exec, exec, s[16:17]
	v_pk_fma_f32 v[230:231], v[90:91], v[186:187], v[194:195]
	v_pk_fma_f32 v[232:233], v[92:93], v[188:189], v[196:197]
	v_pk_fma_f32 v[234:235], v[82:83], v[202:203], v[210:211]
	v_pk_fma_f32 v[236:237], v[84:85], v[204:205], v[212:213]
	v_fmac_f32_dpp v230, v90, v182 row_shr:1 row_mask:0xf bank_mask:0xf
	v_fmac_f32_dpp v231, v91, v183 row_shr:1 row_mask:0xf bank_mask:0xf
	v_fmac_f32_dpp v232, v92, v184 row_shr:1 row_mask:0xf bank_mask:0xf
	v_fmac_f32_dpp v233, v93, v185 row_shr:1 row_mask:0xf bank_mask:0xf
	v_fmac_f32_dpp v234, v82, v198 row_shr:1 row_mask:0xf bank_mask:0xf
	v_fmac_f32_dpp v235, v83, v199 row_shr:1 row_mask:0xf bank_mask:0xf
	v_fmac_f32_dpp v236, v84, v200 row_shr:1 row_mask:0xf bank_mask:0xf
	v_fmac_f32_dpp v237, v85, v201 row_shr:1 row_mask:0xf bank_mask:0xf
	v_fmac_f32_dpp v230, v90, v190 row_shl:1 row_mask:0xf bank_mask:0xf
	v_fmac_f32_dpp v231, v91, v191 row_shl:1 row_mask:0xf bank_mask:0xf
	v_fmac_f32_dpp v232, v92, v192 row_shl:1 row_mask:0xf bank_mask:0xf
	v_fmac_f32_dpp v233, v93, v193 row_shl:1 row_mask:0xf bank_mask:0xf
; __device__ __forceinline__ unsigned cvt_pk_bf16(float lo, float hi) { unsigned r; asm volatile("v_cvt_pk_bf16_f32 %0, %1, %2" : "=v"(r) : "v"(lo), "v"(hi)); return r; }
; __device__ __forceinline__ float sigmoid_f(float x) { return fast_rcp(1.0f + fast_exp2(-1.4426950409f * x)); }
;     __device__ __forceinline__ void operator()(f32x4 (&acc)[2][2][4][2], const Unit& u, int wr, int wc, int fr, int fq) const {
;     ...
;                 for (int m = 0; m < 4; ++m) {
;                     f32x4 cv[2];
; #pragma unroll
;                     for (int bj = 0; bj < 2; ++bj) {
;                         const f32x4 cur = acc[ai][bj][m][n], lo = acc[ai][bj][m > 0 ? m - 1 : 0][n], hi = acc[ai][bj][m < 3 ? m + 1 : 3][n];
;                         f32x4 pv, nv;
; #pragma unroll
;                         for (int idx = 0; idx < 4; ++idx) {
;                             const float y = (fr == 15) ? lo[idx] : cur[idx], z = (fr == 0) ? hi[idx] : cur[idx];
;                             pv[idx] = __int_as_float(__builtin_amdgcn_update_dpp(0, __float_as_int(y), 0x121, 0xf, 0xf, false));
;                             nv[idx] = __int_as_float(__builtin_amdgcn_update_dpp(0, __float_as_int(z), 0x12f, 0xf, 0xf, false));
;                         }
;                         cv[bj] = kc[bj][0] * pv + kc[bj][1] * cur + kc[bj][2] * nv + bc[bj];
;                     }
;                     const int row = row0 + ai * HALF + m * 16;
;                     const bool edge = (m == 0 && fr == 0) || (m == 3 && fr == 15);
;                     if (!edge) { const f32x4 gt = cv[0], vl = cv[1];
;                         u32x2 w; w.x = cvt_pk_bf16(gt[0] * sigmoid_f(gt[0]) * vl[0], gt[1] * sigmoid_f(gt[1]) * vl[1]); w.y = cvt_pk_bf16(gt[2] * sigmoid_f(gt[2]) * vl[2], gt[3] * sigmoid_f(gt[3]) * vl[3]);
;                         *(u32x2*)(ACT + (size_t)row * FF + j4) = w; }
	v_fmac_f32_dpp v234, v82, v206 row_shl:1 row_mask:0xf bank_mask:0xf
	v_fmac_f32_dpp v235, v83, v207 row_shl:1 row_mask:0xf bank_mask:0xf
	v_fmac_f32_dpp v236, v84, v208 row_shl:1 row_mask:0xf bank_mask:0xf
	v_fmac_f32_dpp v237, v85, v209 row_shl:1 row_mask:0xf bank_mask:0xf
	v_fmac_f32_dpp v230, v94, v214 row_ror:1 row_mask:0xf bank_mask:0xf
	v_fmac_f32_dpp v231, v95, v215 row_ror:1 row_mask:0xf bank_mask:0xf
	v_fmac_f32_dpp v232, v96, v216 row_ror:1 row_mask:0xf bank_mask:0xf
	v_fmac_f32_dpp v233, v97, v217 row_ror:1 row_mask:0xf bank_mask:0xf
	v_fmac_f32_dpp v234, v86, v218 row_ror:1 row_mask:0xf bank_mask:0xf
	v_fmac_f32_dpp v235, v87, v219 row_ror:1 row_mask:0xf bank_mask:0xf
	v_fmac_f32_dpp v236, v88, v220 row_ror:1 row_mask:0xf bank_mask:0xf
	v_fmac_f32_dpp v237, v89, v221 row_ror:1 row_mask:0xf bank_mask:0xf
	v_fmac_f32_dpp v230, v78, v222 row_ror:15 row_mask:0xf bank_mask:0xf
	v_fmac_f32_dpp v231, v79, v223 row_ror:15 row_mask:0xf bank_mask:0xf
	v_fmac_f32_dpp v232, v80, v224 row_ror:15 row_mask:0xf bank_mask:0xf
	v_fmac_f32_dpp v233, v81, v225 row_ror:15 row_mask:0xf bank_mask:0xf
	v_fmac_f32_dpp v234, v70, v226 row_ror:15 row_mask:0xf bank_mask:0xf
	v_fmac_f32_dpp v235, v71, v227 row_ror:15 row_mask:0xf bank_mask:0xf
	v_fmac_f32_dpp v236, v72, v228 row_ror:15 row_mask:0xf bank_mask:0xf
	v_fmac_f32_dpp v237, v73, v229 row_ror:15 row_mask:0xf bank_mask:0xf
	v_pk_mul_f32 v[174:175], v[230:231], s[34:35]
	v_pk_mul_f32 v[176:177], v[232:233], s[34:35]
	v_exp_f32_e32 v174, v174
	v_exp_f32_e32 v175, v175
	v_exp_f32_e32 v176, v176
	v_exp_f32_e32 v177, v177
	v_pk_add_f32 v[174:175], v[174:175], s[36:37]
	v_pk_add_f32 v[176:177], v[176:177], s[36:37]
	v_rcp_f32_e32 v174, v174
	v_rcp_f32_e32 v175, v175
	v_rcp_f32_e32 v176, v176
	v_rcp_f32_e32 v177, v177
	v_pk_mul_f32 v[174:175], v[230:231], v[174:175]
	v_pk_mul_f32 v[176:177], v[232:233], v[176:177]
	v_pk_mul_f32 v[174:175], v[174:175], v[234:235]
	v_pk_mul_f32 v[176:177], v[176:177], v[236:237]
	v_cvt_pk_bf16_f32 v178, v174, v175
	v_cvt_pk_bf16_f32 v179, v176, v177
	v_add_u32_e32 v239, 0x183000, v238
	global_store_dwordx2 v239, v[178:179], s[30:31]
	v_pk_fma_f32 v[230:231], v[78:79], v[186:187], v[194:195]
	v_pk_fma_f32 v[232:233], v[80:81], v[188:189], v[196:197]
	v_pk_fma_f32 v[234:235], v[70:71], v[202:203], v[210:211]
	v_pk_fma_f32 v[236:237], v[72:73], v[204:205], v[212:213]
	v_fmac_f32_dpp v230, v78, v182 row_shr:1 row_mask:0xf bank_mask:0xf
	v_fmac_f32_dpp v231, v79, v183 row_shr:1 row_mask:0xf bank_mask:0xf
	v_fmac_f32_dpp v232, v80, v184 row_shr:1 row_mask:0xf bank_mask:0xf
	v_fmac_f32_dpp v233, v81, v185 row_shr:1 row_mask:0xf bank_mask:0xf
	v_fmac_f32_dpp v234, v70, v198 row_shr:1 row_mask:0xf bank_mask:0xf
	v_fmac_f32_dpp v235, v71, v199 row_shr:1 row_mask:0xf bank_mask:0xf
	v_fmac_f32_dpp v236, v72, v200 row_shr:1 row_mask:0xf bank_mask:0xf
	v_fmac_f32_dpp v237, v73, v201 row_shr:1 row_mask:0xf bank_mask:0xf
	v_fmac_f32_dpp v230, v78, v190 row_shl:1 row_mask:0xf bank_mask:0xf
	v_fmac_f32_dpp v231, v79, v191 row_shl:1 row_mask:0xf bank_mask:0xf
	v_fmac_f32_dpp v232, v80, v192 row_shl:1 row_mask:0xf bank_mask:0xf
	v_fmac_f32_dpp v233, v81, v193 row_shl:1 row_mask:0xf bank_mask:0xf
	v_fmac_f32_dpp v234, v70, v206 row_shl:1 row_mask:0xf bank_mask:0xf
	v_fmac_f32_dpp v235, v71, v207 row_shl:1 row_mask:0xf bank_mask:0xf
	v_fmac_f32_dpp v236, v72, v208 row_shl:1 row_mask:0xf bank_mask:0xf
	v_fmac_f32_dpp v237, v73, v209 row_shl:1 row_mask:0xf bank_mask:0xf
	v_fmac_f32_dpp v230, v90, v214 row_ror:1 row_mask:0xf bank_mask:0xf
	v_fmac_f32_dpp v231, v91, v215 row_ror:1 row_mask:0xf bank_mask:0xf
	v_fmac_f32_dpp v232, v92, v216 row_ror:1 row_mask:0xf bank_mask:0xf
	v_fmac_f32_dpp v233, v93, v217 row_ror:1 row_mask:0xf bank_mask:0xf
	v_fmac_f32_dpp v234, v82, v218 row_ror:1 row_mask:0xf bank_mask:0xf
	v_fmac_f32_dpp v235, v83, v219 row_ror:1 row_mask:0xf bank_mask:0xf
	v_fmac_f32_dpp v236, v84, v220 row_ror:1 row_mask:0xf bank_mask:0xf
	v_fmac_f32_dpp v237, v85, v221 row_ror:1 row_mask:0xf bank_mask:0xf
	v_fmac_f32_dpp v230, v74, v222 row_ror:15 row_mask:0xf bank_mask:0xf
	v_fmac_f32_dpp v231, v75, v223 row_ror:15 row_mask:0xf bank_mask:0xf
	v_fmac_f32_dpp v232, v76, v224 row_ror:15 row_mask:0xf bank_mask:0xf
	v_fmac_f32_dpp v233, v77, v225 row_ror:15 row_mask:0xf bank_mask:0xf
	v_fmac_f32_dpp v234, v66, v226 row_ror:15 row_mask:0xf bank_mask:0xf
	v_fmac_f32_dpp v235, v67, v227 row_ror:15 row_mask:0xf bank_mask:0xf
	v_fmac_f32_dpp v236, v68, v228 row_ror:15 row_mask:0xf bank_mask:0xf
	v_fmac_f32_dpp v237, v69, v229 row_ror:15 row_mask:0xf bank_mask:0xf
	v_pk_mul_f32 v[174:175], v[230:231], s[34:35]
	v_pk_mul_f32 v[176:177], v[232:233], s[34:35]
	v_exp_f32_e32 v174, v174
	v_exp_f32_e32 v175, v175
	v_exp_f32_e32 v176, v176
	v_exp_f32_e32 v177, v177
	v_pk_add_f32 v[174:175], v[174:175], s[36:37]
	v_pk_add_f32 v[176:177], v[176:177], s[36:37]
	v_rcp_f32_e32 v174, v174
	v_rcp_f32_e32 v175, v175
	v_rcp_f32_e32 v176, v176
	v_rcp_f32_e32 v177, v177
	v_pk_mul_f32 v[174:175], v[230:231], v[174:175]
	v_pk_mul_f32 v[176:177], v[232:233], v[176:177]
	v_pk_mul_f32 v[174:175], v[174:175], v[234:235]
	v_pk_mul_f32 v[176:177], v[176:177], v[236:237]
	v_cvt_pk_bf16_f32 v180, v174, v175
	v_cvt_pk_bf16_f32 v181, v176, v177
	v_add_u32_e32 v239, 0x1ae000, v238
	global_store_dwordx2 v239, v[180:181], s[30:31]
	v_pk_fma_f32 v[230:231], v[74:75], v[186:187], v[194:195]
	v_pk_fma_f32 v[232:233], v[76:77], v[188:189], v[196:197]
	v_pk_fma_f32 v[234:235], v[66:67], v[202:203], v[210:211]
	v_pk_fma_f32 v[236:237], v[68:69], v[204:205], v[212:213]
	v_fmac_f32_dpp v230, v74, v182 row_shr:1 row_mask:0xf bank_mask:0xf
; __device__ __forceinline__ unsigned cvt_pk_bf16(float lo, float hi) { unsigned r; asm volatile("v_cvt_pk_bf16_f32 %0, %1, %2" : "=v"(r) : "v"(lo), "v"(hi)); return r; }
; __device__ __forceinline__ float sigmoid_f(float x) { return fast_rcp(1.0f + fast_exp2(-1.4426950409f * x)); }
;     __device__ __forceinline__ void operator()(f32x4 (&acc)[2][2][4][2], const Unit& u, int wr, int wc, int fr, int fq) const {
;     ...
;                 for (int m = 0; m < 4; ++m) {
;                     f32x4 cv[2];
; #pragma unroll
;                     for (int bj = 0; bj < 2; ++bj) {
;                         const f32x4 cur = acc[ai][bj][m][n], lo = acc[ai][bj][m > 0 ? m - 1 : 0][n], hi = acc[ai][bj][m < 3 ? m + 1 : 3][n];
;                         f32x4 pv, nv;
; #pragma unroll
;                         for (int idx = 0; idx < 4; ++idx) {
;                             const float y = (fr == 15) ? lo[idx] : cur[idx], z = (fr == 0) ? hi[idx] : cur[idx];
;                             pv[idx] = __int_as_float(__builtin_amdgcn_update_dpp(0, __float_as_int(y), 0x121, 0xf, 0xf, false));
;                             nv[idx] = __int_as_float(__builtin_amdgcn_update_dpp(0, __float_as_int(z), 0x12f, 0xf, 0xf, false));
;                         }
;                         cv[bj] = kc[bj][0] * pv + kc[bj][1] * cur + kc[bj][2] * nv + bc[bj];
;                     }
;                     const int row = row0 + ai * HALF + m * 16;
;                     const bool edge = (m == 0 && fr == 0) || (m == 3 && fr == 15);
;                     if (!edge) { const f32x4 gt = cv[0], vl = cv[1];
;                         u32x2 w; w.x = cvt_pk_bf16(gt[0] * sigmoid_f(gt[0]) * vl[0], gt[1] * sigmoid_f(gt[1]) * vl[1]); w.y = cvt_pk_bf16(gt[2] * sigmoid_f(gt[2]) * vl[2], gt[3] * sigmoid_f(gt[3]) * vl[3]);
;                         *(u32x2*)(ACT + (size_t)row * FF + j4) = w; }
	v_fmac_f32_dpp v231, v75, v183 row_shr:1 row_mask:0xf bank_mask:0xf
	v_fmac_f32_dpp v232, v76, v184 row_shr:1 row_mask:0xf bank_mask:0xf
	v_fmac_f32_dpp v233, v77, v185 row_shr:1 row_mask:0xf bank_mask:0xf
	v_fmac_f32_dpp v234, v66, v198 row_shr:1 row_mask:0xf bank_mask:0xf
	v_fmac_f32_dpp v235, v67, v199 row_shr:1 row_mask:0xf bank_mask:0xf
	v_fmac_f32_dpp v236, v68, v200 row_shr:1 row_mask:0xf bank_mask:0xf
	v_fmac_f32_dpp v237, v69, v201 row_shr:1 row_mask:0xf bank_mask:0xf
	v_fmac_f32_dpp v230, v74, v190 row_shl:1 row_mask:0xf bank_mask:0xf
	v_fmac_f32_dpp v231, v75, v191 row_shl:1 row_mask:0xf bank_mask:0xf
	v_fmac_f32_dpp v232, v76, v192 row_shl:1 row_mask:0xf bank_mask:0xf
	v_fmac_f32_dpp v233, v77, v193 row_shl:1 row_mask:0xf bank_mask:0xf
	v_fmac_f32_dpp v234, v66, v206 row_shl:1 row_mask:0xf bank_mask:0xf
	v_fmac_f32_dpp v235, v67, v207 row_shl:1 row_mask:0xf bank_mask:0xf
	v_fmac_f32_dpp v236, v68, v208 row_shl:1 row_mask:0xf bank_mask:0xf
	v_fmac_f32_dpp v237, v69, v209 row_shl:1 row_mask:0xf bank_mask:0xf
	v_fmac_f32_dpp v230, v78, v214 row_ror:1 row_mask:0xf bank_mask:0xf
	v_fmac_f32_dpp v231, v79, v215 row_ror:1 row_mask:0xf bank_mask:0xf
	v_fmac_f32_dpp v232, v80, v216 row_ror:1 row_mask:0xf bank_mask:0xf
	v_fmac_f32_dpp v233, v81, v217 row_ror:1 row_mask:0xf bank_mask:0xf
	v_fmac_f32_dpp v234, v70, v218 row_ror:1 row_mask:0xf bank_mask:0xf
	v_fmac_f32_dpp v235, v71, v219 row_ror:1 row_mask:0xf bank_mask:0xf
	v_fmac_f32_dpp v236, v72, v220 row_ror:1 row_mask:0xf bank_mask:0xf
	v_fmac_f32_dpp v237, v73, v221 row_ror:1 row_mask:0xf bank_mask:0xf
	v_pk_mul_f32 v[174:175], v[230:231], s[34:35]
	v_pk_mul_f32 v[176:177], v[232:233], s[34:35]
	v_exp_f32_e32 v174, v174
	v_exp_f32_e32 v175, v175
	v_exp_f32_e32 v176, v176
	v_exp_f32_e32 v177, v177
	v_pk_add_f32 v[174:175], v[174:175], s[36:37]
	v_pk_add_f32 v[176:177], v[176:177], s[36:37]
	v_rcp_f32_e32 v174, v174
	v_rcp_f32_e32 v175, v175
	v_rcp_f32_e32 v176, v176
	v_rcp_f32_e32 v177, v177
	v_pk_mul_f32 v[174:175], v[230:231], v[174:175]
	v_pk_mul_f32 v[176:177], v[232:233], v[176:177]
	v_pk_mul_f32 v[174:175], v[174:175], v[234:235]
	v_pk_mul_f32 v[176:177], v[176:177], v[236:237]
	v_cvt_pk_bf16_f32 v178, v174, v175
	v_cvt_pk_bf16_f32 v179, v176, v177
	v_add_u32_e32 v239, 0x1d9000, v238
	s_and_saveexec_b64 s[16:17], s[40:41]
	global_store_dwordx2 v239, v[178:179], s[30:31]
	s_or_b64 exec, exec, s[16:17]
	s_waitcnt vmcnt(4)
	v_cndmask_b32_e64 v214, 0, v126, s[42:43]
	v_cndmask_b32_e64 v215, 0, v127, s[42:43]
	v_cndmask_b32_e64 v216, 0, v128, s[42:43]
	v_cndmask_b32_e64 v217, 0, v129, s[42:43]
	v_cndmask_b32_e64 v218, 0, v122, s[42:43]
	v_cndmask_b32_e64 v219, 0, v123, s[42:43]
	v_cndmask_b32_e64 v220, 0, v124, s[42:43]
	v_cndmask_b32_e64 v221, 0, v125, s[42:43]
	v_cndmask_b32_e64 v222, 0, v110, s[38:39]
	v_cndmask_b32_e64 v223, 0, v111, s[38:39]
	v_cndmask_b32_e64 v224, 0, v112, s[38:39]
	v_cndmask_b32_e64 v225, 0, v113, s[38:39]
	v_cndmask_b32_e64 v226, 0, v102, s[38:39]
	v_cndmask_b32_e64 v227, 0, v103, s[38:39]
	v_cndmask_b32_e64 v228, 0, v104, s[38:39]
	v_cndmask_b32_e64 v229, 0, v105, s[38:39]
	v_pk_fma_f32 v[230:231], v[62:63], v[118:119], v[106:107]
	v_pk_fma_f32 v[232:233], v[64:65], v[120:121], v[108:109]
	v_pk_fma_f32 v[234:235], v[54:55], v[114:115], v[98:99]
	v_pk_fma_f32 v[236:237], v[56:57], v[116:117], v[100:101]
	v_fmac_f32_dpp v230, v62, v126 row_shr:1 row_mask:0xf bank_mask:0xf
	v_fmac_f32_dpp v231, v63, v127 row_shr:1 row_mask:0xf bank_mask:0xf
	v_fmac_f32_dpp v232, v64, v128 row_shr:1 row_mask:0xf bank_mask:0xf
	v_fmac_f32_dpp v233, v65, v129 row_shr:1 row_mask:0xf bank_mask:0xf
	v_fmac_f32_dpp v234, v54, v122 row_shr:1 row_mask:0xf bank_mask:0xf
	v_fmac_f32_dpp v235, v55, v123 row_shr:1 row_mask:0xf bank_mask:0xf
	v_fmac_f32_dpp v236, v56, v124 row_shr:1 row_mask:0xf bank_mask:0xf
	v_fmac_f32_dpp v237, v57, v125 row_shr:1 row_mask:0xf bank_mask:0xf
	v_fmac_f32_dpp v230, v62, v110 row_shl:1 row_mask:0xf bank_mask:0xf
	v_fmac_f32_dpp v231, v63, v111 row_shl:1 row_mask:0xf bank_mask:0xf
	v_fmac_f32_dpp v232, v64, v112 row_shl:1 row_mask:0xf bank_mask:0xf
	v_fmac_f32_dpp v233, v65, v113 row_shl:1 row_mask:0xf bank_mask:0xf
	v_fmac_f32_dpp v234, v54, v102 row_shl:1 row_mask:0xf bank_mask:0xf
	v_fmac_f32_dpp v235, v55, v103 row_shl:1 row_mask:0xf bank_mask:0xf
	v_fmac_f32_dpp v236, v56, v104 row_shl:1 row_mask:0xf bank_mask:0xf
	v_fmac_f32_dpp v237, v57, v105 row_shl:1 row_mask:0xf bank_mask:0xf
	v_fmac_f32_dpp v230, v58, v222 row_ror:15 row_mask:0xf bank_mask:0xf
	v_fmac_f32_dpp v231, v59, v223 row_ror:15 row_mask:0xf bank_mask:0xf
	v_fmac_f32_dpp v232, v60, v224 row_ror:15 row_mask:0xf bank_mask:0xf
	v_fmac_f32_dpp v233, v61, v225 row_ror:15 row_mask:0xf bank_mask:0xf
	v_fmac_f32_dpp v234, v50, v226 row_ror:15 row_mask:0xf bank_mask:0xf
	v_fmac_f32_dpp v235, v51, v227 row_ror:15 row_mask:0xf bank_mask:0xf
	v_fmac_f32_dpp v236, v52, v228 row_ror:15 row_mask:0xf bank_mask:0xf
	v_fmac_f32_dpp v237, v53, v229 row_ror:15 row_mask:0xf bank_mask:0xf
	v_pk_mul_f32 v[174:175], v[230:231], s[34:35]
	v_pk_mul_f32 v[176:177], v[232:233], s[34:35]
	v_exp_f32_e32 v174, v174
	v_exp_f32_e32 v175, v175
	v_exp_f32_e32 v176, v176
	v_exp_f32_e32 v177, v177
	v_pk_add_f32 v[174:175], v[174:175], s[36:37]
	v_pk_add_f32 v[176:177], v[176:177], s[36:37]
	v_rcp_f32_e32 v174, v174
	v_rcp_f32_e32 v175, v175
	v_rcp_f32_e32 v176, v176
	v_rcp_f32_e32 v177, v177
	v_pk_mul_f32 v[174:175], v[230:231], v[174:175]
	v_pk_mul_f32 v[176:177], v[232:233], v[176:177]
	v_pk_mul_f32 v[174:175], v[174:175], v[234:235]
	v_pk_mul_f32 v[176:177], v[176:177], v[236:237]
	v_cvt_pk_bf16_f32 v178, v174, v175
; __device__ __forceinline__ unsigned cvt_pk_bf16(float lo, float hi) { unsigned r; asm volatile("v_cvt_pk_bf16_f32 %0, %1, %2" : "=v"(r) : "v"(lo), "v"(hi)); return r; }
; __device__ __forceinline__ float sigmoid_f(float x) { return fast_rcp(1.0f + fast_exp2(-1.4426950409f * x)); }
;     __device__ __forceinline__ void operator()(f32x4 (&acc)[2][2][4][2], const Unit& u, int wr, int wc, int fr, int fq) const {
;     ...
;                 for (int m = 0; m < 4; ++m) {
;                     f32x4 cv[2];
; #pragma unroll
;                     for (int bj = 0; bj < 2; ++bj) {
;                         const f32x4 cur = acc[ai][bj][m][n], lo = acc[ai][bj][m > 0 ? m - 1 : 0][n], hi = acc[ai][bj][m < 3 ? m + 1 : 3][n];
;                         f32x4 pv, nv;
; #pragma unroll
;                         for (int idx = 0; idx < 4; ++idx) {
;                             const float y = (fr == 15) ? lo[idx] : cur[idx], z = (fr == 0) ? hi[idx] : cur[idx];
;                             pv[idx] = __int_as_float(__builtin_amdgcn_update_dpp(0, __float_as_int(y), 0x121, 0xf, 0xf, false));
;                             nv[idx] = __int_as_float(__builtin_amdgcn_update_dpp(0, __float_as_int(z), 0x12f, 0xf, 0xf, false));
;                         }
;                         cv[bj] = kc[bj][0] * pv + kc[bj][1] * cur + kc[bj][2] * nv + bc[bj];
;                     }
;                     const int row = row0 + ai * HALF + m * 16;
;                     const bool edge = (m == 0 && fr == 0) || (m == 3 && fr == 15);
;                     if (!edge) { const f32x4 gt = cv[0], vl = cv[1];
;                         u32x2 w; w.x = cvt_pk_bf16(gt[0] * sigmoid_f(gt[0]) * vl[0], gt[1] * sigmoid_f(gt[1]) * vl[1]); w.y = cvt_pk_bf16(gt[2] * sigmoid_f(gt[2]) * vl[2], gt[3] * sigmoid_f(gt[3]) * vl[3]);
;                         *(u32x2*)(ACT + (size_t)row * FF + j4) = w; }
	v_cvt_pk_bf16_f32 v179, v176, v177
	s_and_saveexec_b64 s[16:17], s[44:45]
	global_store_dwordx2 v238, v[178:179], s[30:31] offset:8
	s_or_b64 exec, exec, s[16:17]
	v_pk_fma_f32 v[230:231], v[58:59], v[118:119], v[106:107]
	v_pk_fma_f32 v[232:233], v[60:61], v[120:121], v[108:109]
	v_pk_fma_f32 v[234:235], v[50:51], v[114:115], v[98:99]
	v_pk_fma_f32 v[236:237], v[52:53], v[116:117], v[100:101]
	v_fmac_f32_dpp v230, v58, v126 row_shr:1 row_mask:0xf bank_mask:0xf
	v_fmac_f32_dpp v231, v59, v127 row_shr:1 row_mask:0xf bank_mask:0xf
	v_fmac_f32_dpp v232, v60, v128 row_shr:1 row_mask:0xf bank_mask:0xf
	v_fmac_f32_dpp v233, v61, v129 row_shr:1 row_mask:0xf bank_mask:0xf
	v_fmac_f32_dpp v234, v50, v122 row_shr:1 row_mask:0xf bank_mask:0xf
	v_fmac_f32_dpp v235, v51, v123 row_shr:1 row_mask:0xf bank_mask:0xf
	v_fmac_f32_dpp v236, v52, v124 row_shr:1 row_mask:0xf bank_mask:0xf
	v_fmac_f32_dpp v237, v53, v125 row_shr:1 row_mask:0xf bank_mask:0xf
	v_fmac_f32_dpp v230, v58, v110 row_shl:1 row_mask:0xf bank_mask:0xf
	v_fmac_f32_dpp v231, v59, v111 row_shl:1 row_mask:0xf bank_mask:0xf
	v_fmac_f32_dpp v232, v60, v112 row_shl:1 row_mask:0xf bank_mask:0xf
	v_fmac_f32_dpp v233, v61, v113 row_shl:1 row_mask:0xf bank_mask:0xf
	v_fmac_f32_dpp v234, v50, v102 row_shl:1 row_mask:0xf bank_mask:0xf
	v_fmac_f32_dpp v235, v51, v103 row_shl:1 row_mask:0xf bank_mask:0xf
	v_fmac_f32_dpp v236, v52, v104 row_shl:1 row_mask:0xf bank_mask:0xf
	v_fmac_f32_dpp v237, v53, v105 row_shl:1 row_mask:0xf bank_mask:0xf
	v_fmac_f32_dpp v230, v62, v214 row_ror:1 row_mask:0xf bank_mask:0xf
	v_fmac_f32_dpp v231, v63, v215 row_ror:1 row_mask:0xf bank_mask:0xf
	v_fmac_f32_dpp v232, v64, v216 row_ror:1 row_mask:0xf bank_mask:0xf
	v_fmac_f32_dpp v233, v65, v217 row_ror:1 row_mask:0xf bank_mask:0xf
	v_fmac_f32_dpp v234, v54, v218 row_ror:1 row_mask:0xf bank_mask:0xf
	v_fmac_f32_dpp v235, v55, v219 row_ror:1 row_mask:0xf bank_mask:0xf
	v_fmac_f32_dpp v236, v56, v220 row_ror:1 row_mask:0xf bank_mask:0xf
	v_fmac_f32_dpp v237, v57, v221 row_ror:1 row_mask:0xf bank_mask:0xf
	v_fmac_f32_dpp v230, v46, v222 row_ror:15 row_mask:0xf bank_mask:0xf
	v_fmac_f32_dpp v231, v47, v223 row_ror:15 row_mask:0xf bank_mask:0xf
	v_fmac_f32_dpp v232, v48, v224 row_ror:15 row_mask:0xf bank_mask:0xf
	v_fmac_f32_dpp v233, v49, v225 row_ror:15 row_mask:0xf bank_mask:0xf
	v_fmac_f32_dpp v234, v38, v226 row_ror:15 row_mask:0xf bank_mask:0xf
	v_fmac_f32_dpp v235, v39, v227 row_ror:15 row_mask:0xf bank_mask:0xf
	v_fmac_f32_dpp v236, v40, v228 row_ror:15 row_mask:0xf bank_mask:0xf
	v_fmac_f32_dpp v237, v41, v229 row_ror:15 row_mask:0xf bank_mask:0xf
	v_pk_mul_f32 v[174:175], v[230:231], s[34:35]
	v_pk_mul_f32 v[176:177], v[232:233], s[34:35]
	v_exp_f32_e32 v174, v174
	v_exp_f32_e32 v175, v175
	v_exp_f32_e32 v176, v176
	v_exp_f32_e32 v177, v177
	v_pk_add_f32 v[174:175], v[174:175], s[36:37]
	v_pk_add_f32 v[176:177], v[176:177], s[36:37]
	v_rcp_f32_e32 v174, v174
	v_rcp_f32_e32 v175, v175
	v_rcp_f32_e32 v176, v176
	v_rcp_f32_e32 v177, v177
	v_pk_mul_f32 v[174:175], v[230:231], v[174:175]
	v_pk_mul_f32 v[176:177], v[232:233], v[176:177]
	v_pk_mul_f32 v[174:175], v[174:175], v[234:235]
	v_pk_mul_f32 v[176:177], v[176:177], v[236:237]
	v_cvt_pk_bf16_f32 v180, v174, v175
	v_cvt_pk_bf16_f32 v181, v176, v177
	v_add_u32_e32 v239, 0x2b000, v238
	global_store_dwordx2 v239, v[180:181], s[30:31] offset:8
	v_pk_fma_f32 v[230:231], v[46:47], v[118:119], v[106:107]
	v_pk_fma_f32 v[232:233], v[48:49], v[120:121], v[108:109]
	v_pk_fma_f32 v[234:235], v[38:39], v[114:115], v[98:99]
	v_pk_fma_f32 v[236:237], v[40:41], v[116:117], v[100:101]
	v_fmac_f32_dpp v230, v46, v126 row_shr:1 row_mask:0xf bank_mask:0xf
	v_fmac_f32_dpp v231, v47, v127 row_shr:1 row_mask:0xf bank_mask:0xf
	v_fmac_f32_dpp v232, v48, v128 row_shr:1 row_mask:0xf bank_mask:0xf
	v_fmac_f32_dpp v233, v49, v129 row_shr:1 row_mask:0xf bank_mask:0xf
	v_fmac_f32_dpp v234, v38, v122 row_shr:1 row_mask:0xf bank_mask:0xf
	v_fmac_f32_dpp v235, v39, v123 row_shr:1 row_mask:0xf bank_mask:0xf
	v_fmac_f32_dpp v236, v40, v124 row_shr:1 row_mask:0xf bank_mask:0xf
	v_fmac_f32_dpp v237, v41, v125 row_shr:1 row_mask:0xf bank_mask:0xf
	v_fmac_f32_dpp v230, v46, v110 row_shl:1 row_mask:0xf bank_mask:0xf
	v_fmac_f32_dpp v231, v47, v111 row_shl:1 row_mask:0xf bank_mask:0xf
	v_fmac_f32_dpp v232, v48, v112 row_shl:1 row_mask:0xf bank_mask:0xf
	v_fmac_f32_dpp v233, v49, v113 row_shl:1 row_mask:0xf bank_mask:0xf
	v_fmac_f32_dpp v234, v38, v102 row_shl:1 row_mask:0xf bank_mask:0xf
	v_fmac_f32_dpp v235, v39, v103 row_shl:1 row_mask:0xf bank_mask:0xf
	v_fmac_f32_dpp v236, v40, v104 row_shl:1 row_mask:0xf bank_mask:0xf
	v_fmac_f32_dpp v237, v41, v105 row_shl:1 row_mask:0xf bank_mask:0xf
	v_fmac_f32_dpp v230, v58, v214 row_ror:1 row_mask:0xf bank_mask:0xf
	v_fmac_f32_dpp v231, v59, v215 row_ror:1 row_mask:0xf bank_mask:0xf
	v_fmac_f32_dpp v232, v60, v216 row_ror:1 row_mask:0xf bank_mask:0xf
	v_fmac_f32_dpp v233, v61, v217 row_ror:1 row_mask:0xf bank_mask:0xf
	v_fmac_f32_dpp v234, v50, v218 row_ror:1 row_mask:0xf bank_mask:0xf
	v_fmac_f32_dpp v235, v51, v219 row_ror:1 row_mask:0xf bank_mask:0xf
	v_fmac_f32_dpp v236, v52, v220 row_ror:1 row_mask:0xf bank_mask:0xf
	v_fmac_f32_dpp v237, v53, v221 row_ror:1 row_mask:0xf bank_mask:0xf
	v_fmac_f32_dpp v230, v42, v222 row_ror:15 row_mask:0xf bank_mask:0xf
	v_fmac_f32_dpp v231, v43, v223 row_ror:15 row_mask:0xf bank_mask:0xf
	v_fmac_f32_dpp v232, v44, v224 row_ror:15 row_mask:0xf bank_mask:0xf
	v_fmac_f32_dpp v233, v45, v225 row_ror:15 row_mask:0xf bank_mask:0xf
	v_fmac_f32_dpp v234, v34, v226 row_ror:15 row_mask:0xf bank_mask:0xf
; __device__ __forceinline__ unsigned cvt_pk_bf16(float lo, float hi) { unsigned r; asm volatile("v_cvt_pk_bf16_f32 %0, %1, %2" : "=v"(r) : "v"(lo), "v"(hi)); return r; }
; __device__ __forceinline__ float sigmoid_f(float x) { return fast_rcp(1.0f + fast_exp2(-1.4426950409f * x)); }
;     __device__ __forceinline__ void operator()(f32x4 (&acc)[2][2][4][2], const Unit& u, int wr, int wc, int fr, int fq) const {
;     ...
;                 for (int m = 0; m < 4; ++m) {
;                     f32x4 cv[2];
; #pragma unroll
;                     for (int bj = 0; bj < 2; ++bj) {
;                         const f32x4 cur = acc[ai][bj][m][n], lo = acc[ai][bj][m > 0 ? m - 1 : 0][n], hi = acc[ai][bj][m < 3 ? m + 1 : 3][n];
;                         f32x4 pv, nv;
; #pragma unroll
;                         for (int idx = 0; idx < 4; ++idx) {
;                             const float y = (fr == 15) ? lo[idx] : cur[idx], z = (fr == 0) ? hi[idx] : cur[idx];
;                             pv[idx] = __int_as_float(__builtin_amdgcn_update_dpp(0, __float_as_int(y), 0x121, 0xf, 0xf, false));
;                             nv[idx] = __int_as_float(__builtin_amdgcn_update_dpp(0, __float_as_int(z), 0x12f, 0xf, 0xf, false));
;                         }
;                         cv[bj] = kc[bj][0] * pv + kc[bj][1] * cur + kc[bj][2] * nv + bc[bj];
;                     }
;                     const int row = row0 + ai * HALF + m * 16;
;                     const bool edge = (m == 0 && fr == 0) || (m == 3 && fr == 15);
;                     if (!edge) { const f32x4 gt = cv[0], vl = cv[1];
;                         u32x2 w; w.x = cvt_pk_bf16(gt[0] * sigmoid_f(gt[0]) * vl[0], gt[1] * sigmoid_f(gt[1]) * vl[1]); w.y = cvt_pk_bf16(gt[2] * sigmoid_f(gt[2]) * vl[2], gt[3] * sigmoid_f(gt[3]) * vl[3]);
;                         *(u32x2*)(ACT + (size_t)row * FF + j4) = w; }
	v_fmac_f32_dpp v235, v35, v227 row_ror:15 row_mask:0xf bank_mask:0xf
	v_fmac_f32_dpp v236, v36, v228 row_ror:15 row_mask:0xf bank_mask:0xf
	v_fmac_f32_dpp v237, v37, v229 row_ror:15 row_mask:0xf bank_mask:0xf
	v_pk_mul_f32 v[174:175], v[230:231], s[34:35]
	v_pk_mul_f32 v[176:177], v[232:233], s[34:35]
	v_exp_f32_e32 v174, v174
	v_exp_f32_e32 v175, v175
	v_exp_f32_e32 v176, v176
	v_exp_f32_e32 v177, v177
	v_pk_add_f32 v[174:175], v[174:175], s[36:37]
	v_pk_add_f32 v[176:177], v[176:177], s[36:37]
	v_rcp_f32_e32 v174, v174
	v_rcp_f32_e32 v175, v175
	v_rcp_f32_e32 v176, v176
	v_rcp_f32_e32 v177, v177
	v_pk_mul_f32 v[174:175], v[230:231], v[174:175]
	v_pk_mul_f32 v[176:177], v[232:233], v[176:177]
	v_pk_mul_f32 v[174:175], v[174:175], v[234:235]
	v_pk_mul_f32 v[176:177], v[176:177], v[236:237]
	v_cvt_pk_bf16_f32 v178, v174, v175
	v_cvt_pk_bf16_f32 v179, v176, v177
	v_add_u32_e32 v239, 0x56000, v238
	global_store_dwordx2 v239, v[178:179], s[30:31] offset:8
	v_pk_fma_f32 v[230:231], v[42:43], v[118:119], v[106:107]
	v_pk_fma_f32 v[232:233], v[44:45], v[120:121], v[108:109]
	v_pk_fma_f32 v[234:235], v[34:35], v[114:115], v[98:99]
	v_pk_fma_f32 v[236:237], v[36:37], v[116:117], v[100:101]
	v_fmac_f32_dpp v230, v42, v126 row_shr:1 row_mask:0xf bank_mask:0xf
	v_fmac_f32_dpp v231, v43, v127 row_shr:1 row_mask:0xf bank_mask:0xf
	v_fmac_f32_dpp v232, v44, v128 row_shr:1 row_mask:0xf bank_mask:0xf
	v_fmac_f32_dpp v233, v45, v129 row_shr:1 row_mask:0xf bank_mask:0xf
	v_fmac_f32_dpp v234, v34, v122 row_shr:1 row_mask:0xf bank_mask:0xf
	v_fmac_f32_dpp v235, v35, v123 row_shr:1 row_mask:0xf bank_mask:0xf
	v_fmac_f32_dpp v236, v36, v124 row_shr:1 row_mask:0xf bank_mask:0xf
	v_fmac_f32_dpp v237, v37, v125 row_shr:1 row_mask:0xf bank_mask:0xf
	v_fmac_f32_dpp v230, v42, v110 row_shl:1 row_mask:0xf bank_mask:0xf
	v_fmac_f32_dpp v231, v43, v111 row_shl:1 row_mask:0xf bank_mask:0xf
	v_fmac_f32_dpp v232, v44, v112 row_shl:1 row_mask:0xf bank_mask:0xf
	v_fmac_f32_dpp v233, v45, v113 row_shl:1 row_mask:0xf bank_mask:0xf
	v_fmac_f32_dpp v234, v34, v102 row_shl:1 row_mask:0xf bank_mask:0xf
	v_fmac_f32_dpp v235, v35, v103 row_shl:1 row_mask:0xf bank_mask:0xf
	v_fmac_f32_dpp v236, v36, v104 row_shl:1 row_mask:0xf bank_mask:0xf
	v_fmac_f32_dpp v237, v37, v105 row_shl:1 row_mask:0xf bank_mask:0xf
	v_fmac_f32_dpp v230, v46, v214 row_ror:1 row_mask:0xf bank_mask:0xf
	v_fmac_f32_dpp v231, v47, v215 row_ror:1 row_mask:0xf bank_mask:0xf
	v_fmac_f32_dpp v232, v48, v216 row_ror:1 row_mask:0xf bank_mask:0xf
	v_fmac_f32_dpp v233, v49, v217 row_ror:1 row_mask:0xf bank_mask:0xf
	v_fmac_f32_dpp v234, v38, v218 row_ror:1 row_mask:0xf bank_mask:0xf
	v_fmac_f32_dpp v235, v39, v219 row_ror:1 row_mask:0xf bank_mask:0xf
	v_fmac_f32_dpp v236, v40, v220 row_ror:1 row_mask:0xf bank_mask:0xf
	v_fmac_f32_dpp v237, v41, v221 row_ror:1 row_mask:0xf bank_mask:0xf
	v_pk_mul_f32 v[174:175], v[230:231], s[34:35]
	v_pk_mul_f32 v[176:177], v[232:233], s[34:35]
	v_exp_f32_e32 v174, v174
	v_exp_f32_e32 v175, v175
	v_exp_f32_e32 v176, v176
	v_exp_f32_e32 v177, v177
	v_pk_add_f32 v[174:175], v[174:175], s[36:37]
	v_pk_add_f32 v[176:177], v[176:177], s[36:37]
	v_rcp_f32_e32 v174, v174
	v_rcp_f32_e32 v175, v175
	v_rcp_f32_e32 v176, v176
	v_rcp_f32_e32 v177, v177
	v_pk_mul_f32 v[174:175], v[230:231], v[174:175]
	v_pk_mul_f32 v[176:177], v[232:233], v[176:177]
	v_pk_mul_f32 v[174:175], v[174:175], v[234:235]
	v_pk_mul_f32 v[176:177], v[176:177], v[236:237]
	v_cvt_pk_bf16_f32 v180, v174, v175
	v_cvt_pk_bf16_f32 v181, v176, v177
	v_add_u32_e32 v239, 0x81000, v238
	s_and_saveexec_b64 s[16:17], s[40:41]
	global_store_dwordx2 v239, v[180:181], s[30:31] offset:8
	s_or_b64 exec, exec, s[16:17]
	v_pk_fma_f32 v[230:231], v[30:31], v[118:119], v[106:107]
	v_pk_fma_f32 v[232:233], v[32:33], v[120:121], v[108:109]
	v_pk_fma_f32 v[234:235], v[22:23], v[114:115], v[98:99]
	v_pk_fma_f32 v[236:237], v[24:25], v[116:117], v[100:101]
	v_fmac_f32_dpp v230, v30, v126 row_shr:1 row_mask:0xf bank_mask:0xf
	v_fmac_f32_dpp v231, v31, v127 row_shr:1 row_mask:0xf bank_mask:0xf
	v_fmac_f32_dpp v232, v32, v128 row_shr:1 row_mask:0xf bank_mask:0xf
	v_fmac_f32_dpp v233, v33, v129 row_shr:1 row_mask:0xf bank_mask:0xf
	v_fmac_f32_dpp v234, v22, v122 row_shr:1 row_mask:0xf bank_mask:0xf
	v_fmac_f32_dpp v235, v23, v123 row_shr:1 row_mask:0xf bank_mask:0xf
	v_fmac_f32_dpp v236, v24, v124 row_shr:1 row_mask:0xf bank_mask:0xf
	v_fmac_f32_dpp v237, v25, v125 row_shr:1 row_mask:0xf bank_mask:0xf
	v_fmac_f32_dpp v230, v30, v110 row_shl:1 row_mask:0xf bank_mask:0xf
	v_fmac_f32_dpp v231, v31, v111 row_shl:1 row_mask:0xf bank_mask:0xf
	v_fmac_f32_dpp v232, v32, v112 row_shl:1 row_mask:0xf bank_mask:0xf
	v_fmac_f32_dpp v233, v33, v113 row_shl:1 row_mask:0xf bank_mask:0xf
	v_fmac_f32_dpp v234, v22, v102 row_shl:1 row_mask:0xf bank_mask:0xf
	v_fmac_f32_dpp v235, v23, v103 row_shl:1 row_mask:0xf bank_mask:0xf
	v_fmac_f32_dpp v236, v24, v104 row_shl:1 row_mask:0xf bank_mask:0xf
	v_fmac_f32_dpp v237, v25, v105 row_shl:1 row_mask:0xf bank_mask:0xf
	v_fmac_f32_dpp v230, v26, v222 row_ror:15 row_mask:0xf bank_mask:0xf
	v_fmac_f32_dpp v231, v27, v223 row_ror:15 row_mask:0xf bank_mask:0xf
	v_fmac_f32_dpp v232, v28, v224 row_ror:15 row_mask:0xf bank_mask:0xf
	v_fmac_f32_dpp v233, v29, v225 row_ror:15 row_mask:0xf bank_mask:0xf
	v_fmac_f32_dpp v234, v18, v226 row_ror:15 row_mask:0xf bank_mask:0xf
	v_fmac_f32_dpp v235, v19, v227 row_ror:15 row_mask:0xf bank_mask:0xf
	v_fmac_f32_dpp v236, v20, v228 row_ror:15 row_mask:0xf bank_mask:0xf
	v_fmac_f32_dpp v237, v21, v229 row_ror:15 row_mask:0xf bank_mask:0xf
	v_pk_mul_f32 v[174:175], v[230:231], s[34:35]
; __device__ __forceinline__ unsigned cvt_pk_bf16(float lo, float hi) { unsigned r; asm volatile("v_cvt_pk_bf16_f32 %0, %1, %2" : "=v"(r) : "v"(lo), "v"(hi)); return r; }
; __device__ __forceinline__ float sigmoid_f(float x) { return fast_rcp(1.0f + fast_exp2(-1.4426950409f * x)); }
;     __device__ __forceinline__ void operator()(f32x4 (&acc)[2][2][4][2], const Unit& u, int wr, int wc, int fr, int fq) const {
;     ...
;                 for (int m = 0; m < 4; ++m) {
;                     f32x4 cv[2];
; #pragma unroll
;                     for (int bj = 0; bj < 2; ++bj) {
;                         const f32x4 cur = acc[ai][bj][m][n], lo = acc[ai][bj][m > 0 ? m - 1 : 0][n], hi = acc[ai][bj][m < 3 ? m + 1 : 3][n];
;                         f32x4 pv, nv;
; #pragma unroll
;                         for (int idx = 0; idx < 4; ++idx) {
;                             const float y = (fr == 15) ? lo[idx] : cur[idx], z = (fr == 0) ? hi[idx] : cur[idx];
;                             pv[idx] = __int_as_float(__builtin_amdgcn_update_dpp(0, __float_as_int(y), 0x121, 0xf, 0xf, false));
;                             nv[idx] = __int_as_float(__builtin_amdgcn_update_dpp(0, __float_as_int(z), 0x12f, 0xf, 0xf, false));
;                         }
;                         cv[bj] = kc[bj][0] * pv + kc[bj][1] * cur + kc[bj][2] * nv + bc[bj];
;                     }
;                     const int row = row0 + ai * HALF + m * 16;
;                     const bool edge = (m == 0 && fr == 0) || (m == 3 && fr == 15);
;                     if (!edge) { const f32x4 gt = cv[0], vl = cv[1];
;                         u32x2 w; w.x = cvt_pk_bf16(gt[0] * sigmoid_f(gt[0]) * vl[0], gt[1] * sigmoid_f(gt[1]) * vl[1]); w.y = cvt_pk_bf16(gt[2] * sigmoid_f(gt[2]) * vl[2], gt[3] * sigmoid_f(gt[3]) * vl[3]);
;                         *(u32x2*)(ACT + (size_t)row * FF + j4) = w; }
	v_pk_mul_f32 v[176:177], v[232:233], s[34:35]
	v_exp_f32_e32 v174, v174
	v_exp_f32_e32 v175, v175
	v_exp_f32_e32 v176, v176
	v_exp_f32_e32 v177, v177
	v_pk_add_f32 v[174:175], v[174:175], s[36:37]
	v_pk_add_f32 v[176:177], v[176:177], s[36:37]
	v_rcp_f32_e32 v174, v174
	v_rcp_f32_e32 v175, v175
	v_rcp_f32_e32 v176, v176
	v_rcp_f32_e32 v177, v177
	v_pk_mul_f32 v[174:175], v[230:231], v[174:175]
	v_pk_mul_f32 v[176:177], v[232:233], v[176:177]
	v_pk_mul_f32 v[174:175], v[174:175], v[234:235]
	v_pk_mul_f32 v[176:177], v[176:177], v[236:237]
	v_cvt_pk_bf16_f32 v180, v174, v175
	v_cvt_pk_bf16_f32 v181, v176, v177
	v_add_u32_e32 v239, 0x158000, v238
	s_and_saveexec_b64 s[16:17], s[44:45]
	global_store_dwordx2 v239, v[180:181], s[30:31] offset:8
	s_or_b64 exec, exec, s[16:17]
	v_pk_fma_f32 v[230:231], v[26:27], v[118:119], v[106:107]
	v_pk_fma_f32 v[232:233], v[28:29], v[120:121], v[108:109]
	v_pk_fma_f32 v[234:235], v[18:19], v[114:115], v[98:99]
	v_pk_fma_f32 v[236:237], v[20:21], v[116:117], v[100:101]
	v_fmac_f32_dpp v230, v26, v126 row_shr:1 row_mask:0xf bank_mask:0xf
	v_fmac_f32_dpp v231, v27, v127 row_shr:1 row_mask:0xf bank_mask:0xf
	v_fmac_f32_dpp v232, v28, v128 row_shr:1 row_mask:0xf bank_mask:0xf
	v_fmac_f32_dpp v233, v29, v129 row_shr:1 row_mask:0xf bank_mask:0xf
	v_fmac_f32_dpp v234, v18, v122 row_shr:1 row_mask:0xf bank_mask:0xf
	v_fmac_f32_dpp v235, v19, v123 row_shr:1 row_mask:0xf bank_mask:0xf
	v_fmac_f32_dpp v236, v20, v124 row_shr:1 row_mask:0xf bank_mask:0xf
	v_fmac_f32_dpp v237, v21, v125 row_shr:1 row_mask:0xf bank_mask:0xf
	v_fmac_f32_dpp v230, v26, v110 row_shl:1 row_mask:0xf bank_mask:0xf
	v_fmac_f32_dpp v231, v27, v111 row_shl:1 row_mask:0xf bank_mask:0xf
	v_fmac_f32_dpp v232, v28, v112 row_shl:1 row_mask:0xf bank_mask:0xf
	v_fmac_f32_dpp v233, v29, v113 row_shl:1 row_mask:0xf bank_mask:0xf
	v_fmac_f32_dpp v234, v18, v102 row_shl:1 row_mask:0xf bank_mask:0xf
	v_fmac_f32_dpp v235, v19, v103 row_shl:1 row_mask:0xf bank_mask:0xf
	v_fmac_f32_dpp v236, v20, v104 row_shl:1 row_mask:0xf bank_mask:0xf
	v_fmac_f32_dpp v237, v21, v105 row_shl:1 row_mask:0xf bank_mask:0xf
	v_fmac_f32_dpp v230, v30, v214 row_ror:1 row_mask:0xf bank_mask:0xf
	v_fmac_f32_dpp v231, v31, v215 row_ror:1 row_mask:0xf bank_mask:0xf
	v_fmac_f32_dpp v232, v32, v216 row_ror:1 row_mask:0xf bank_mask:0xf
	v_fmac_f32_dpp v233, v33, v217 row_ror:1 row_mask:0xf bank_mask:0xf
	v_fmac_f32_dpp v234, v22, v218 row_ror:1 row_mask:0xf bank_mask:0xf
	v_fmac_f32_dpp v235, v23, v219 row_ror:1 row_mask:0xf bank_mask:0xf
	v_fmac_f32_dpp v236, v24, v220 row_ror:1 row_mask:0xf bank_mask:0xf
	v_fmac_f32_dpp v237, v25, v221 row_ror:1 row_mask:0xf bank_mask:0xf
	v_fmac_f32_dpp v230, v14, v222 row_ror:15 row_mask:0xf bank_mask:0xf
	v_fmac_f32_dpp v231, v15, v223 row_ror:15 row_mask:0xf bank_mask:0xf
	v_fmac_f32_dpp v232, v16, v224 row_ror:15 row_mask:0xf bank_mask:0xf
	v_fmac_f32_dpp v233, v17, v225 row_ror:15 row_mask:0xf bank_mask:0xf
	v_fmac_f32_dpp v234, v6, v226 row_ror:15 row_mask:0xf bank_mask:0xf
	v_fmac_f32_dpp v235, v7, v227 row_ror:15 row_mask:0xf bank_mask:0xf
	v_fmac_f32_dpp v236, v8, v228 row_ror:15 row_mask:0xf bank_mask:0xf
	v_fmac_f32_dpp v237, v9, v229 row_ror:15 row_mask:0xf bank_mask:0xf
	v_pk_mul_f32 v[174:175], v[230:231], s[34:35]
	v_pk_mul_f32 v[176:177], v[232:233], s[34:35]
	v_exp_f32_e32 v174, v174
	v_exp_f32_e32 v175, v175
	v_exp_f32_e32 v176, v176
	v_exp_f32_e32 v177, v177
	v_pk_add_f32 v[174:175], v[174:175], s[36:37]
	v_pk_add_f32 v[176:177], v[176:177], s[36:37]
	v_rcp_f32_e32 v174, v174
	v_rcp_f32_e32 v175, v175
	v_rcp_f32_e32 v176, v176
	v_rcp_f32_e32 v177, v177
	v_pk_mul_f32 v[174:175], v[230:231], v[174:175]
	v_pk_mul_f32 v[176:177], v[232:233], v[176:177]
	v_pk_mul_f32 v[174:175], v[174:175], v[234:235]
	v_pk_mul_f32 v[176:177], v[176:177], v[236:237]
	v_cvt_pk_bf16_f32 v178, v174, v175
	v_cvt_pk_bf16_f32 v179, v176, v177
	v_add_u32_e32 v239, 0x183000, v238
	global_store_dwordx2 v239, v[178:179], s[30:31] offset:8
	v_pk_fma_f32 v[230:231], v[14:15], v[118:119], v[106:107]
	v_pk_fma_f32 v[232:233], v[16:17], v[120:121], v[108:109]
	v_pk_fma_f32 v[234:235], v[6:7], v[114:115], v[98:99]
	v_pk_fma_f32 v[236:237], v[8:9], v[116:117], v[100:101]
	v_fmac_f32_dpp v230, v14, v126 row_shr:1 row_mask:0xf bank_mask:0xf
	v_fmac_f32_dpp v231, v15, v127 row_shr:1 row_mask:0xf bank_mask:0xf
	v_fmac_f32_dpp v232, v16, v128 row_shr:1 row_mask:0xf bank_mask:0xf
	v_fmac_f32_dpp v233, v17, v129 row_shr:1 row_mask:0xf bank_mask:0xf
	v_fmac_f32_dpp v234, v6, v122 row_shr:1 row_mask:0xf bank_mask:0xf
	v_fmac_f32_dpp v235, v7, v123 row_shr:1 row_mask:0xf bank_mask:0xf
	v_fmac_f32_dpp v236, v8, v124 row_shr:1 row_mask:0xf bank_mask:0xf
	v_fmac_f32_dpp v237, v9, v125 row_shr:1 row_mask:0xf bank_mask:0xf
	v_fmac_f32_dpp v230, v14, v110 row_shl:1 row_mask:0xf bank_mask:0xf
	v_fmac_f32_dpp v231, v15, v111 row_shl:1 row_mask:0xf bank_mask:0xf
	v_fmac_f32_dpp v232, v16, v112 row_shl:1 row_mask:0xf bank_mask:0xf
	v_fmac_f32_dpp v233, v17, v113 row_shl:1 row_mask:0xf bank_mask:0xf
	v_fmac_f32_dpp v234, v6, v102 row_shl:1 row_mask:0xf bank_mask:0xf
	v_fmac_f32_dpp v235, v7, v103 row_shl:1 row_mask:0xf bank_mask:0xf
	v_fmac_f32_dpp v236, v8, v104 row_shl:1 row_mask:0xf bank_mask:0xf
; __device__ __forceinline__ unsigned cvt_pk_bf16(float lo, float hi) { unsigned r; asm volatile("v_cvt_pk_bf16_f32 %0, %1, %2" : "=v"(r) : "v"(lo), "v"(hi)); return r; }
; __device__ __forceinline__ float sigmoid_f(float x) { return fast_rcp(1.0f + fast_exp2(-1.4426950409f * x)); }
; #define PG8_WAIT_V(n) asm volatile("s_waitcnt vmcnt(" #n ")" ::: "memory")
; #define PG8_BAR __builtin_amdgcn_s_barrier()
; template <class Epi, class SchedT, bool ALIGN_EPI, bool SP2>
; __device__ __forceinline__ void gemm_phase(LAS unsigned char* lds, const int ldk, const int nt, const SchedT& S, const Epi& E) {
;     ...
;         cur = nxt; cA = nA; cB = nB; ++ui;
;         if constexpr (ALIGN_EPI) { if (wr == 1) PG8_BAR; }
;     }
;     PG8_WAIT_V(0);
;     if constexpr (!ALIGN_EPI) { if (wr == 0) PG8_BAR; }
;     PG8_BAR;
;     __device__ __forceinline__ void operator()(f32x4 (&acc)[2][2][4][2], const Unit& u, int wr, int wc, int fr, int fq) const {
;     ...
;                 for (int m = 0; m < 4; ++m) {
;                     f32x4 cv[2];
; #pragma unroll
;                     for (int bj = 0; bj < 2; ++bj) {
;                         const f32x4 cur = acc[ai][bj][m][n], lo = acc[ai][bj][m > 0 ? m - 1 : 0][n], hi = acc[ai][bj][m < 3 ? m + 1 : 3][n];
;                         f32x4 pv, nv;
; #pragma unroll
;                         for (int idx = 0; idx < 4; ++idx) {
;                             const float y = (fr == 15) ? lo[idx] : cur[idx], z = (fr == 0) ? hi[idx] : cur[idx];
;                             pv[idx] = __int_as_float(__builtin_amdgcn_update_dpp(0, __float_as_int(y), 0x121, 0xf, 0xf, false));
;                             nv[idx] = __int_as_float(__builtin_amdgcn_update_dpp(0, __float_as_int(z), 0x12f, 0xf, 0xf, false));
;                         }
;                         cv[bj] = kc[bj][0] * pv + kc[bj][1] * cur + kc[bj][2] * nv + bc[bj];
;                     }
;                     const int row = row0 + ai * HALF + m * 16;
;                     const bool edge = (m == 0 && fr == 0) || (m == 3 && fr == 15);
;                     if (!edge) { const f32x4 gt = cv[0], vl = cv[1];
;                         u32x2 w; w.x = cvt_pk_bf16(gt[0] * sigmoid_f(gt[0]) * vl[0], gt[1] * sigmoid_f(gt[1]) * vl[1]); w.y = cvt_pk_bf16(gt[2] * sigmoid_f(gt[2]) * vl[2], gt[3] * sigmoid_f(gt[3]) * vl[3]);
;                         *(u32x2*)(ACT + (size_t)row * FF + j4) = w; }
	v_fmac_f32_dpp v237, v9, v105 row_shl:1 row_mask:0xf bank_mask:0xf
	v_fmac_f32_dpp v230, v26, v214 row_ror:1 row_mask:0xf bank_mask:0xf
	v_fmac_f32_dpp v231, v27, v215 row_ror:1 row_mask:0xf bank_mask:0xf
	v_fmac_f32_dpp v232, v28, v216 row_ror:1 row_mask:0xf bank_mask:0xf
	v_fmac_f32_dpp v233, v29, v217 row_ror:1 row_mask:0xf bank_mask:0xf
	v_fmac_f32_dpp v234, v18, v218 row_ror:1 row_mask:0xf bank_mask:0xf
	v_fmac_f32_dpp v235, v19, v219 row_ror:1 row_mask:0xf bank_mask:0xf
	v_fmac_f32_dpp v236, v20, v220 row_ror:1 row_mask:0xf bank_mask:0xf
	v_fmac_f32_dpp v237, v21, v221 row_ror:1 row_mask:0xf bank_mask:0xf
	v_fmac_f32_dpp v230, v10, v222 row_ror:15 row_mask:0xf bank_mask:0xf
	v_fmac_f32_dpp v231, v11, v223 row_ror:15 row_mask:0xf bank_mask:0xf
	v_fmac_f32_dpp v232, v12, v224 row_ror:15 row_mask:0xf bank_mask:0xf
	v_fmac_f32_dpp v233, v13, v225 row_ror:15 row_mask:0xf bank_mask:0xf
	v_fmac_f32_dpp v234, v2, v226 row_ror:15 row_mask:0xf bank_mask:0xf
	v_fmac_f32_dpp v235, v3, v227 row_ror:15 row_mask:0xf bank_mask:0xf
	v_fmac_f32_dpp v236, v4, v228 row_ror:15 row_mask:0xf bank_mask:0xf
	v_fmac_f32_dpp v237, v5, v229 row_ror:15 row_mask:0xf bank_mask:0xf
	v_pk_mul_f32 v[174:175], v[230:231], s[34:35]
	v_pk_mul_f32 v[176:177], v[232:233], s[34:35]
	v_exp_f32_e32 v174, v174
	v_exp_f32_e32 v175, v175
	v_exp_f32_e32 v176, v176
	v_exp_f32_e32 v177, v177
	v_pk_add_f32 v[174:175], v[174:175], s[36:37]
	v_pk_add_f32 v[176:177], v[176:177], s[36:37]
	v_rcp_f32_e32 v174, v174
	v_rcp_f32_e32 v175, v175
	v_rcp_f32_e32 v176, v176
	v_rcp_f32_e32 v177, v177
	v_pk_mul_f32 v[174:175], v[230:231], v[174:175]
	v_pk_mul_f32 v[176:177], v[232:233], v[176:177]
	v_pk_mul_f32 v[174:175], v[174:175], v[234:235]
	v_pk_mul_f32 v[176:177], v[176:177], v[236:237]
	v_cvt_pk_bf16_f32 v180, v174, v175
	v_cvt_pk_bf16_f32 v181, v176, v177
	v_add_u32_e32 v239, 0x1ae000, v238
	global_store_dwordx2 v239, v[180:181], s[30:31] offset:8
	v_pk_fma_f32 v[230:231], v[10:11], v[118:119], v[106:107]
	v_pk_fma_f32 v[232:233], v[12:13], v[120:121], v[108:109]
	v_pk_fma_f32 v[234:235], v[2:3], v[114:115], v[98:99]
	v_pk_fma_f32 v[236:237], v[4:5], v[116:117], v[100:101]
	v_fmac_f32_dpp v230, v10, v126 row_shr:1 row_mask:0xf bank_mask:0xf
	v_fmac_f32_dpp v231, v11, v127 row_shr:1 row_mask:0xf bank_mask:0xf
	v_fmac_f32_dpp v232, v12, v128 row_shr:1 row_mask:0xf bank_mask:0xf
	v_fmac_f32_dpp v233, v13, v129 row_shr:1 row_mask:0xf bank_mask:0xf
	v_fmac_f32_dpp v234, v2, v122 row_shr:1 row_mask:0xf bank_mask:0xf
	v_fmac_f32_dpp v235, v3, v123 row_shr:1 row_mask:0xf bank_mask:0xf
	v_fmac_f32_dpp v236, v4, v124 row_shr:1 row_mask:0xf bank_mask:0xf
	v_fmac_f32_dpp v237, v5, v125 row_shr:1 row_mask:0xf bank_mask:0xf
	v_fmac_f32_dpp v230, v10, v110 row_shl:1 row_mask:0xf bank_mask:0xf
	v_fmac_f32_dpp v231, v11, v111 row_shl:1 row_mask:0xf bank_mask:0xf
	v_fmac_f32_dpp v232, v12, v112 row_shl:1 row_mask:0xf bank_mask:0xf
	v_fmac_f32_dpp v233, v13, v113 row_shl:1 row_mask:0xf bank_mask:0xf
	v_fmac_f32_dpp v234, v2, v102 row_shl:1 row_mask:0xf bank_mask:0xf
	v_fmac_f32_dpp v235, v3, v103 row_shl:1 row_mask:0xf bank_mask:0xf
	v_fmac_f32_dpp v236, v4, v104 row_shl:1 row_mask:0xf bank_mask:0xf
	v_fmac_f32_dpp v237, v5, v105 row_shl:1 row_mask:0xf bank_mask:0xf
	v_fmac_f32_dpp v230, v14, v214 row_ror:1 row_mask:0xf bank_mask:0xf
	v_fmac_f32_dpp v231, v15, v215 row_ror:1 row_mask:0xf bank_mask:0xf
	v_fmac_f32_dpp v232, v16, v216 row_ror:1 row_mask:0xf bank_mask:0xf
	v_fmac_f32_dpp v233, v17, v217 row_ror:1 row_mask:0xf bank_mask:0xf
	v_fmac_f32_dpp v234, v6, v218 row_ror:1 row_mask:0xf bank_mask:0xf
	v_fmac_f32_dpp v235, v7, v219 row_ror:1 row_mask:0xf bank_mask:0xf
	v_fmac_f32_dpp v236, v8, v220 row_ror:1 row_mask:0xf bank_mask:0xf
	v_fmac_f32_dpp v237, v9, v221 row_ror:1 row_mask:0xf bank_mask:0xf
	v_pk_mul_f32 v[174:175], v[230:231], s[34:35]
	v_pk_mul_f32 v[176:177], v[232:233], s[34:35]
	v_exp_f32_e32 v174, v174
	v_exp_f32_e32 v175, v175
	v_exp_f32_e32 v176, v176
	v_exp_f32_e32 v177, v177
	v_pk_add_f32 v[174:175], v[174:175], s[36:37]
	v_pk_add_f32 v[176:177], v[176:177], s[36:37]
	v_rcp_f32_e32 v174, v174
	v_rcp_f32_e32 v175, v175
	v_rcp_f32_e32 v176, v176
	v_rcp_f32_e32 v177, v177
	v_pk_mul_f32 v[174:175], v[230:231], v[174:175]
	v_pk_mul_f32 v[176:177], v[232:233], v[176:177]
	v_pk_mul_f32 v[174:175], v[174:175], v[234:235]
	v_pk_mul_f32 v[176:177], v[176:177], v[236:237]
	v_cvt_pk_bf16_f32 v178, v174, v175
	v_cvt_pk_bf16_f32 v179, v176, v177
	v_add_u32_e32 v239, 0x1d9000, v238
	s_and_saveexec_b64 s[16:17], s[40:41]
	global_store_dwordx2 v239, v[178:179], s[30:31] offset:8
	s_or_b64 exec, exec, s[16:17]
	s_movk_i32 s94, 0x1000
	s_movk_i32 s95, 0x3000
	s_and_b64 vcc, exec, s[50:51]
	s_mov_b64 s[12:13], -1
	s_cbranch_vccnz .LBB0_746
.LBB0_788:
	s_branch .LBB0_745
.LBB0_790:
	s_setprio 0
	s_waitcnt vmcnt(0)
	v_readlane_b32 s88, v163, 21
	v_readlane_b32 s90, v163, 27
	v_readlane_b32 s84, v163, 29
	v_readlane_b32 s60, v163, 31
	v_readlane_b32 s89, v163, 22
	v_readlane_b32 s80, v163, 23
	v_readlane_b32 s91, v163, 28
	v_readlane_b32 s85, v163, 30
	v_readlane_b32 s61, v163, 32
	v_readlane_b32 s92, v163, 33
	s_mov_b32 s86, 0x20000
	s_mov_b32 s87, 0x28000
	v_mov_b32_e32 v242, v162
	s_barrier
	v_readlane_b32 s81, v163, 24
